# GEMM epilogue stores write-through (sc1) to cut grid-barrier L2 writeback; RWKV chunk loop: operand LDS reads issued right after barrier
# speedup vs baseline: 1.1382x; 1.0078x over previous
; __device__ __forceinline__ void rwkv_scan_job(const P& p, int job, char* smc) {
;     ...
;   typedef float v2f __attribute__((ext_vector_type(2)));
;   v2f Sa = {0.f, 0.f}, Sb = {0.f, 0.f};
;   const int il = wave * 4 + (lane >> 4);
;   const float m0 = ((lane & 15) == 0) ? 1.f : 0.f;
;   const bool b3 = lane & 8, b2 = lane & 4, b1 = lane & 2, b0 = lane & 1;
;   const int NCH = SEQL / RW_TC;
;   for (int c = 0; c < NCH; c++) {
;     const bool more = (c + 1) < NCH;
;     if (more) gload(c + 1);
;     const RwBuf& bf = bufs[c & 1];
;     float* yb = ybuf + (c & 1) * 256;
;     float yv[RW_TC];
;     float4 o_dec[3], o_kk[3], o_kka[3], o_kp[3], o_wr[3];
;     float o_vi[3];
;     float2 o_c[3];
;     ...
;     RW_LD(0, 0);
;     RW_LD(1, 1);
; #pragma unroll
;     for (int t = 0; t < RW_TC; t++) {
;       if (t + 2 < RW_TC) RW_LD((t + 2) % 3, t + 2);
;       const float4 dec = o_dec[t % 3], kk = o_kk[t % 3], kka = o_kka[t % 3], kp = o_kp[t % 3], wr = o_wr[t % 3];
.LBB0_159:
	s_or_b64 exec, exec, s[10:11]
	s_cmp_eq_u32 s62, 0
	s_cselect_b64 s[68:69], -1, 0
	s_lshl_b32 s61, s61, 2
	v_lshrrev_b32_e32 v26, 4, v112
	v_writelane_b32 v229, s68, 53
	s_add_u32 s60, s26, s61
	v_bfi_b32 v28, -4, v24, v26
	v_and_b32_e32 v26, 8, v112
	v_writelane_b32 v229, s69, 54
	s_addc_u32 s61, s27, 0
	v_cmp_eq_u32_e64 s[10:11], 0, v26
	v_and_b32_e32 v26, 4, v112
	v_writelane_b32 v229, s60, 47
	v_cmp_eq_u32_e64 s[12:13], 0, v26
	v_and_b32_e32 v26, 2, v112
	v_writelane_b32 v229, s61, 48
	v_cmp_eq_u32_e64 s[14:15], 0, v26
	v_and_b32_e32 v26, 1, v112
	v_readlane_b32 s68, v229, 33
	v_cmp_eq_u32_e64 s[16:17], 0, v26
	s_lshl_b64 vcc, s[6:7], 23
	v_lshlrev_b64 v[26:27], 11, v[24:25]
	s_lshl_b32 s61, s68, 5
	v_lshl_add_u64 v[26:27], vcc, 0, v[26:27]
	s_and_b32 s61, s61, 0x380
	v_or_b32_e32 v26, s61, v26
	s_lshl_b32 s61, s62, 5
	s_add_u32 s8, s8, 16
	s_addc_u32 s9, s9, 0
	v_lshlrev_b32_e32 v29, 1, v36
	v_lshl_add_u64 v[98:99], s[8:9], 0, v[24:25]
	s_lshl_b64 s[8:9], s[6:7], 22
	v_or3_b32 v26, v26, s61, v29
	s_add_u32 s8, s22, s8
	v_lshl_add_u64 v[94:95], s[30:31], 0, v[26:27]
	v_lshlrev_b64 v[26:27], 10, v[24:25]
	s_addc_u32 s9, s23, s9
	v_lshl_add_u64 v[100:101], s[8:9], 0, v[26:27]
	s_mul_hi_i32 s7, s6, 0x1600000
	s_mul_i32 s6, s6, 0x1600000
	v_readlane_b32 s8, v230, 61
	s_add_u32 s6, s8, s6
	v_readlane_b32 s8, v230, 62
	s_addc_u32 s7, s8, s7
	v_lshl_add_u64 v[96:97], v[24:25], 0, 16
	v_mov_b64_e32 v[26:27], s[6:7]
	s_mov_b32 s4, 0
	v_lshlrev_b32_e32 v119, 6, v36
	v_mad_i64_i32 v[102:103], s[6:7], v24, s56, v[26:27]
	s_mov_b64 s[8:9], 0
	v_lshlrev_b32_e32 v97, 2, v28
	v_mov_b32_e32 v33, v32
	v_mov_b32_e32 v34, v32
	v_mov_b32_e32 v35, v32
	s_waitcnt lgkmcnt(0)
	s_barrier
	s_add_i32 s62, s4, 1
	s_and_b32 s4, s4, 1
	s_mul_i32 vcc_lo, s4, 0x5480
	v_lshl_add_u32 v126, v113, 2, vcc_lo
	v_add_u32_e32 v48, vcc_lo, v97
	v_add_u32_e32 v128, 0x5000, v48
	s_lshl_b32 s61, s4, 10
	ds_read_b128 v[144:147], v126 offset:0
	ds_read_b128 v[148:151], v126 offset:4096
	ds_read_b128 v[152:155], v126 offset:8192
	ds_read_b128 v[156:159], v126 offset:12288
	ds_read_b128 v[160:163], v126 offset:16384
	ds_read2_b32 v[184:185], v128 offset0:0 offset1:16
	ds_read_b128 v[164:167], v126 offset:256
	ds_read_b128 v[168:171], v126 offset:4352
	ds_read_b128 v[172:175], v126 offset:8448
	ds_read_b128 v[176:179], v126 offset:12544
	ds_read_b128 v[180:183], v126 offset:16640
	v_readlane_b32 s69, v229, 34
	s_branch .LBB0_162

; __device__ __forceinline__ u16 f2bf(float f) { return (u16)(pack2(f, 0.f) & 0xffffu); }
; __device__ __forceinline__ void rwkv_scan_job(const P& p, int job, char* smc) {
;     ...
;     if (more) stage(bufs[(c + 1) & 1]);
;     __syncthreads();
;     {
;       const int tt = tid >> 4, ii = tid & 15;
;       const size_t t = (size_t)b * SEQL + c * RW_TC + tt;
;       p.A[t * 1024 + h * 64 + rq * 16 + ii] = f2bf(yb[tt * 16 + ii]);
;     }
.LBB0_161:
	v_lshl_add_u32 v37, v112, 2, s61
	s_waitcnt lgkmcnt(0)
	s_barrier
	ds_read_b32 v37, v37 offset:43264
	s_add_u32 s8, s8, 16
	s_addc_u32 s9, s9, 0
	s_mov_b64 s[6:7], 0x8000
	s_mov_b32 s4, s62
	s_cmpk_eq_i32 s8, 0x1000
	s_cbranch_scc1 .Lrw_last
	s_add_i32 s62, s4, 1
	s_and_b32 s4, s4, 1
	s_mul_i32 vcc_lo, s4, 0x5480
	v_lshl_add_u32 v126, v113, 2, vcc_lo
	v_add_u32_e32 v48, vcc_lo, v97
	v_add_u32_e32 v128, 0x5000, v48
	s_lshl_b32 s61, s4, 10
	ds_read_b128 v[144:147], v126 offset:0
	ds_read_b128 v[148:151], v126 offset:4096
	ds_read_b128 v[152:155], v126 offset:8192
	ds_read_b128 v[156:159], v126 offset:12288
	ds_read_b128 v[160:163], v126 offset:16384
	ds_read2_b32 v[184:185], v128 offset0:0 offset1:16
	ds_read_b128 v[164:167], v126 offset:256
	ds_read_b128 v[168:171], v126 offset:4352
	ds_read_b128 v[172:175], v126 offset:8448
	ds_read_b128 v[176:179], v126 offset:12544
	ds_read_b128 v[180:183], v126 offset:16640
	s_waitcnt lgkmcnt(11)
	v_cvt_pk_bf16_f32 v24, v37, s0
	s_nop 0
	global_store_short v[94:95], v24, off
	v_lshl_add_u64 v[94:95], v[94:95], 0, s[6:7]
	v_lshl_add_u64 v[100:101], v[100:101], 0, s[64:65]
	v_lshl_add_u64 v[102:103], v[102:103], 0, s[66:67]
	s_branch .LBB0_162
.Lrw_last:
	s_waitcnt lgkmcnt(0)
	v_cvt_pk_bf16_f32 v24, v37, s0
	s_nop 0
	global_store_short v[94:95], v24, off
	s_branch .LBB0_172

; __device__ __forceinline__ void rwkv_scan_job(const P& p, int job, char* smc) {
;     ...
;     RW_LD(0, 0);
;     RW_LD(1, 1);
; #pragma unroll
;     for (int t = 0; t < RW_TC; t++) {
;       if (t + 2 < RW_TC) RW_LD((t + 2) % 3, t + 2);
;       const float4 dec = o_dec[t % 3], kk = o_kk[t % 3], kka = o_kka[t % 3], kp = o_kp[t % 3], wr = o_wr[t % 3];
;       const float vi = o_vi[t % 3], c1 = o_c[t % 3].x, c2 = o_c[t % 3].y;
;       const v2f kk0 = {kk.x, kk.y}, kk1 = {kk.z, kk.w}, wr0 = {wr.x, wr.y}, wr1 = {wr.z, wr.w};
;       v2f ps = Sa * kk0 + Sb * kk1;
;       v2f py = Sa * wr0 + Sb * wr1;
;       float sa = ps.x + ps.y, yd = py.x + py.y;
;       sa = sum16(sa);
;       yv[t] = yd + m0 * (vi * c2 - sa * c1);
;       const v2f dec0 = {dec.x, dec.y}, dec1 = {dec.z, dec.w}, ka0 = {kka.x, kka.y}, ka1 = {kka.z, kka.w},
;                 kp0 = {kp.x, kp.y}, kp1 = {kp.z, kp.w};
;       const v2f sav = {sa, sa}, viv = {vi, vi};
;       Sa = Sa * dec0 - sav * ka0 + viv * kp0;
;       Sb = Sb * dec1 - sav * ka1 + viv * kp1;
;     }
.LBB0_164:
	s_waitcnt lgkmcnt(5)
	v_pk_mul_f32 v[52:53], v[32:33], v[148:149]
	v_pk_mul_f32 v[60:61], v[156:157], v[184:185] op_sel_hi:[1,0]
	v_pk_fma_f32 v[52:53], v[34:35], v[150:151], v[52:53]
	ds_read_b128 v[232:235], v126 offset:512
	v_add_f32_e32 v56, v52, v53
	v_pk_mul_f32 v[62:63], v[158:159], v[184:185] op_sel_hi:[1,0]
	ds_read_b128 v[236:239], v126 offset:4608
	v_add_f32_dpp v56, v56, v56 quad_perm:[1,0,3,2] row_mask:0xf bank_mask:0xf bound_ctrl:1
	ds_read_b128 v[240:243], v126 offset:8704
	ds_read_b128 v[244:247], v126 offset:12800
	v_add_f32_dpp v56, v56, v56 quad_perm:[2,3,0,1] row_mask:0xf bank_mask:0xf bound_ctrl:1
	ds_read_b128 v[248:251], v126 offset:16896
	ds_read2_b32 v[186:187], v128 offset0:32 offset1:48
	v_add_f32_dpp v56, v56, v56 row_half_mirror row_mask:0xf bank_mask:0xf bound_ctrl:1
	s_nop 0
	s_nop 0
	v_add_f32_dpp v56, v56, v56 row_mirror row_mask:0xf bank_mask:0xf bound_ctrl:1
	v_pk_fma_f32 v[60:61], v[152:153], v[56:57], v[60:61] op_sel_hi:[1,0,1] neg_lo:[1,0,0] neg_hi:[1,0,0]
	v_pk_fma_f32 v[62:63], v[154:155], v[56:57], v[62:63] op_sel_hi:[1,0,1] neg_lo:[1,0,0] neg_hi:[1,0,0]
	v_pk_fma_f32 v[32:33], v[32:33], v[144:145], v[60:61]
	v_pk_fma_f32 v[34:35], v[34:35], v[146:147], v[62:63]
	s_waitcnt lgkmcnt(6)
	v_pk_mul_f32 v[54:55], v[32:33], v[168:169]
	v_pk_mul_f32 v[68:69], v[34:35], v[162:163]
	v_pk_fma_f32 v[54:55], v[34:35], v[170:171], v[54:55]
	ds_read_b128 v[144:147], v126 offset:768
	v_add_f32_e32 v58, v54, v55
	v_pk_fma_f32 v[68:69], v[32:33], v[160:161], v[68:69]
	ds_read_b128 v[148:151], v126 offset:4864
	v_add_f32_dpp v58, v58, v58 quad_perm:[1,0,3,2] row_mask:0xf bank_mask:0xf bound_ctrl:1
	v_add_f32_e32 v36, v68, v69
	ds_read_b128 v[152:155], v126 offset:8960
	v_add_f32_dpp v58, v58, v58 quad_perm:[2,3,0,1] row_mask:0xf bank_mask:0xf bound_ctrl:1
	v_pk_mul_f32 v[64:65], v[176:177], v[184:185] op_sel:[0,1] op_sel_hi:[1,1]
	ds_read_b128 v[156:159], v126 offset:13056
	v_add_f32_dpp v58, v58, v58 row_half_mirror row_mask:0xf bank_mask:0xf bound_ctrl:1
	v_pk_mul_f32 v[66:67], v[178:179], v[184:185] op_sel:[0,1] op_sel_hi:[1,1]
	ds_read_b128 v[160:163], v126 offset:17152
	v_add_f32_dpp v58, v58, v58 row_mirror row_mask:0xf bank_mask:0xf bound_ctrl:1
	v_pk_fma_f32 v[64:65], v[172:173], v[58:59], v[64:65] op_sel_hi:[1,0,1] neg_lo:[1,0,0] neg_hi:[1,0,0]
	v_pk_fma_f32 v[66:67], v[174:175], v[58:59], v[66:67] op_sel_hi:[1,0,1] neg_lo:[1,0,0] neg_hi:[1,0,0]
	v_pk_fma_f32 v[32:33], v[32:33], v[164:165], v[64:65]
	v_pk_fma_f32 v[34:35], v[34:35], v[166:167], v[66:67]
	s_waitcnt lgkmcnt(5)
	v_pk_mul_f32 v[52:53], v[32:33], v[236:237]
	v_pk_mul_f32 v[70:71], v[34:35], v[182:183]
	v_pk_fma_f32 v[52:53], v[34:35], v[238:239], v[52:53]
	ds_read_b128 v[164:167], v126 offset:1024
	v_add_f32_e32 v56, v52, v53
	v_pk_fma_f32 v[70:71], v[32:33], v[180:181], v[70:71]
	ds_read_b128 v[168:171], v126 offset:5120
	v_add_f32_dpp v56, v56, v56 quad_perm:[1,0,3,2] row_mask:0xf bank_mask:0xf bound_ctrl:1
	v_add_f32_e32 v37, v70, v71
	ds_read_b128 v[172:175], v126 offset:9216
	v_add_f32_dpp v56, v56, v56 quad_perm:[2,3,0,1] row_mask:0xf bank_mask:0xf bound_ctrl:1
	v_pk_mul_f32 v[60:61], v[244:245], v[186:187] op_sel_hi:[1,0]
	ds_read_b128 v[176:179], v126 offset:13312
	v_add_f32_dpp v56, v56, v56 row_half_mirror row_mask:0xf bank_mask:0xf bound_ctrl:1
	v_pk_mul_f32 v[62:63], v[246:247], v[186:187] op_sel_hi:[1,0]
	ds_read_b128 v[180:183], v126 offset:17408
	v_add_f32_dpp v56, v56, v56 row_mirror row_mask:0xf bank_mask:0xf bound_ctrl:1
	ds_read2_b32 v[188:189], v128 offset0:64 offset1:80
	v_pk_fma_f32 v[60:61], v[240:241], v[56:57], v[60:61] op_sel_hi:[1,0,1] neg_lo:[1,0,0] neg_hi:[1,0,0]
	v_pk_fma_f32 v[62:63], v[242:243], v[56:57], v[62:63] op_sel_hi:[1,0,1] neg_lo:[1,0,0] neg_hi:[1,0,0]
	v_pk_fma_f32 v[32:33], v[32:33], v[232:233], v[60:61]
	v_pk_fma_f32 v[34:35], v[34:35], v[234:235], v[62:63]
	s_waitcnt lgkmcnt(6)
	v_pk_mul_f32 v[54:55], v[32:33], v[148:149]
	v_pk_mul_f32 v[68:69], v[34:35], v[250:251]
	v_pk_fma_f32 v[54:55], v[34:35], v[150:151], v[54:55]
	ds_read_b128 v[232:235], v126 offset:1280
	v_add_f32_e32 v58, v54, v55
	v_pk_fma_f32 v[68:69], v[32:33], v[248:249], v[68:69]
	ds_read_b128 v[236:239], v126 offset:5376
	v_add_f32_dpp v58, v58, v58 quad_perm:[1,0,3,2] row_mask:0xf bank_mask:0xf bound_ctrl:1
	v_add_f32_e32 v38, v68, v69
	ds_read_b128 v[240:243], v126 offset:9472
	v_add_f32_dpp v58, v58, v58 quad_perm:[2,3,0,1] row_mask:0xf bank_mask:0xf bound_ctrl:1
	v_pk_mul_f32 v[64:65], v[156:157], v[186:187] op_sel:[0,1] op_sel_hi:[1,1]
	ds_read_b128 v[244:247], v126 offset:13568
	v_add_f32_dpp v58, v58, v58 row_half_mirror row_mask:0xf bank_mask:0xf bound_ctrl:1
	v_pk_mul_f32 v[66:67], v[158:159], v[186:187] op_sel:[0,1] op_sel_hi:[1,1]
	ds_read_b128 v[248:251], v126 offset:17664
	v_add_f32_dpp v58, v58, v58 row_mirror row_mask:0xf bank_mask:0xf bound_ctrl:1
	v_pk_fma_f32 v[64:65], v[152:153], v[58:59], v[64:65] op_sel_hi:[1,0,1] neg_lo:[1,0,0] neg_hi:[1,0,0]
	v_pk_fma_f32 v[66:67], v[154:155], v[58:59], v[66:67] op_sel_hi:[1,0,1] neg_lo:[1,0,0] neg_hi:[1,0,0]
	v_pk_fma_f32 v[32:33], v[32:33], v[144:145], v[64:65]
	v_pk_fma_f32 v[34:35], v[34:35], v[146:147], v[66:67]
	s_waitcnt lgkmcnt(5)
; __device__ __forceinline__ void rwkv_scan_job(const P& p, int job, char* smc) {
;     ...
;     for (int t = 0; t < RW_TC; t++) {
;       if (t + 2 < RW_TC) RW_LD((t + 2) % 3, t + 2);
;       const float4 dec = o_dec[t % 3], kk = o_kk[t % 3], kka = o_kka[t % 3], kp = o_kp[t % 3], wr = o_wr[t % 3];
;       const float vi = o_vi[t % 3], c1 = o_c[t % 3].x, c2 = o_c[t % 3].y;
;       const v2f kk0 = {kk.x, kk.y}, kk1 = {kk.z, kk.w}, wr0 = {wr.x, wr.y}, wr1 = {wr.z, wr.w};
;       v2f ps = Sa * kk0 + Sb * kk1;
;       v2f py = Sa * wr0 + Sb * wr1;
;       float sa = ps.x + ps.y, yd = py.x + py.y;
;       sa = sum16(sa);
;       yv[t] = yd + m0 * (vi * c2 - sa * c1);
;       const v2f dec0 = {dec.x, dec.y}, dec1 = {dec.z, dec.w}, ka0 = {kka.x, kka.y}, ka1 = {kka.z, kka.w},
;                 kp0 = {kp.x, kp.y}, kp1 = {kp.z, kp.w};
;       const v2f sav = {sa, sa}, viv = {vi, vi};
;       Sa = Sa * dec0 - sav * ka0 + viv * kp0;
;       Sb = Sb * dec1 - sav * ka1 + viv * kp1;
;     }
	v_pk_mul_f32 v[52:53], v[32:33], v[168:169]
	v_pk_mul_f32 v[70:71], v[34:35], v[162:163]
	v_pk_fma_f32 v[52:53], v[34:35], v[170:171], v[52:53]
	ds_read_b128 v[144:147], v126 offset:1536
	v_add_f32_e32 v56, v52, v53
	v_pk_fma_f32 v[70:71], v[32:33], v[160:161], v[70:71]
	ds_read_b128 v[148:151], v126 offset:5632
	v_add_f32_dpp v56, v56, v56 quad_perm:[1,0,3,2] row_mask:0xf bank_mask:0xf bound_ctrl:1
	v_add_f32_e32 v39, v70, v71
	ds_read_b128 v[152:155], v126 offset:9728
	v_add_f32_dpp v56, v56, v56 quad_perm:[2,3,0,1] row_mask:0xf bank_mask:0xf bound_ctrl:1
	v_pk_mul_f32 v[60:61], v[176:177], v[188:189] op_sel_hi:[1,0]
	ds_read_b128 v[156:159], v126 offset:13824
	v_add_f32_dpp v56, v56, v56 row_half_mirror row_mask:0xf bank_mask:0xf bound_ctrl:1
	v_pk_mul_f32 v[62:63], v[178:179], v[188:189] op_sel_hi:[1,0]
	ds_read_b128 v[160:163], v126 offset:17920
	v_add_f32_dpp v56, v56, v56 row_mirror row_mask:0xf bank_mask:0xf bound_ctrl:1
	ds_read2_b32 v[184:185], v128 offset0:96 offset1:112
	v_pk_fma_f32 v[60:61], v[172:173], v[56:57], v[60:61] op_sel_hi:[1,0,1] neg_lo:[1,0,0] neg_hi:[1,0,0]
	v_pk_fma_f32 v[62:63], v[174:175], v[56:57], v[62:63] op_sel_hi:[1,0,1] neg_lo:[1,0,0] neg_hi:[1,0,0]
	v_pk_fma_f32 v[32:33], v[32:33], v[164:165], v[60:61]
	v_pk_fma_f32 v[34:35], v[34:35], v[166:167], v[62:63]
	s_waitcnt lgkmcnt(6)
	v_pk_mul_f32 v[54:55], v[32:33], v[236:237]
	v_pk_mul_f32 v[68:69], v[34:35], v[182:183]
	v_pk_fma_f32 v[54:55], v[34:35], v[238:239], v[54:55]
	ds_read_b128 v[164:167], v126 offset:1792
	v_add_f32_e32 v58, v54, v55
	v_pk_fma_f32 v[68:69], v[32:33], v[180:181], v[68:69]
	ds_read_b128 v[168:171], v126 offset:5888
	v_add_f32_dpp v58, v58, v58 quad_perm:[1,0,3,2] row_mask:0xf bank_mask:0xf bound_ctrl:1
	v_add_f32_e32 v40, v68, v69
	ds_read_b128 v[172:175], v126 offset:9984
	v_add_f32_dpp v58, v58, v58 quad_perm:[2,3,0,1] row_mask:0xf bank_mask:0xf bound_ctrl:1
	v_pk_mul_f32 v[64:65], v[244:245], v[188:189] op_sel:[0,1] op_sel_hi:[1,1]
	ds_read_b128 v[176:179], v126 offset:14080
	v_add_f32_dpp v58, v58, v58 row_half_mirror row_mask:0xf bank_mask:0xf bound_ctrl:1
	v_pk_mul_f32 v[66:67], v[246:247], v[188:189] op_sel:[0,1] op_sel_hi:[1,1]
	ds_read_b128 v[180:183], v126 offset:18176
	v_add_f32_dpp v58, v58, v58 row_mirror row_mask:0xf bank_mask:0xf bound_ctrl:1
	v_pk_fma_f32 v[64:65], v[240:241], v[58:59], v[64:65] op_sel_hi:[1,0,1] neg_lo:[1,0,0] neg_hi:[1,0,0]
	v_pk_fma_f32 v[66:67], v[242:243], v[58:59], v[66:67] op_sel_hi:[1,0,1] neg_lo:[1,0,0] neg_hi:[1,0,0]
	v_pk_fma_f32 v[32:33], v[32:33], v[232:233], v[64:65]
	v_pk_fma_f32 v[34:35], v[34:35], v[234:235], v[66:67]
	s_waitcnt lgkmcnt(5)
	v_pk_mul_f32 v[52:53], v[32:33], v[148:149]
	v_pk_mul_f32 v[70:71], v[34:35], v[250:251]
	v_pk_fma_f32 v[52:53], v[34:35], v[150:151], v[52:53]
	ds_read_b128 v[232:235], v126 offset:2048
	v_add_f32_e32 v56, v52, v53
	v_pk_fma_f32 v[70:71], v[32:33], v[248:249], v[70:71]
	ds_read_b128 v[236:239], v126 offset:6144
	v_add_f32_dpp v56, v56, v56 quad_perm:[1,0,3,2] row_mask:0xf bank_mask:0xf bound_ctrl:1
	v_add_f32_e32 v41, v70, v71
	ds_read_b128 v[240:243], v126 offset:10240
	v_add_f32_dpp v56, v56, v56 quad_perm:[2,3,0,1] row_mask:0xf bank_mask:0xf bound_ctrl:1
	v_pk_mul_f32 v[60:61], v[156:157], v[184:185] op_sel_hi:[1,0]
	ds_read_b128 v[244:247], v126 offset:14336
	v_add_f32_dpp v56, v56, v56 row_half_mirror row_mask:0xf bank_mask:0xf bound_ctrl:1
	v_pk_mul_f32 v[62:63], v[158:159], v[184:185] op_sel_hi:[1,0]
	ds_read_b128 v[248:251], v126 offset:18432
	v_add_f32_dpp v56, v56, v56 row_mirror row_mask:0xf bank_mask:0xf bound_ctrl:1
	ds_read2_b32 v[186:187], v128 offset0:128 offset1:144
	v_pk_fma_f32 v[60:61], v[152:153], v[56:57], v[60:61] op_sel_hi:[1,0,1] neg_lo:[1,0,0] neg_hi:[1,0,0]
	v_pk_fma_f32 v[62:63], v[154:155], v[56:57], v[62:63] op_sel_hi:[1,0,1] neg_lo:[1,0,0] neg_hi:[1,0,0]
	v_pk_fma_f32 v[32:33], v[32:33], v[144:145], v[60:61]
	v_pk_fma_f32 v[34:35], v[34:35], v[146:147], v[62:63]
	s_waitcnt lgkmcnt(6)
	v_pk_mul_f32 v[54:55], v[32:33], v[168:169]
	v_pk_mul_f32 v[68:69], v[34:35], v[162:163]
	v_pk_fma_f32 v[54:55], v[34:35], v[170:171], v[54:55]
	ds_read_b128 v[144:147], v126 offset:2304
	v_add_f32_e32 v58, v54, v55
	v_pk_fma_f32 v[68:69], v[32:33], v[160:161], v[68:69]
	ds_read_b128 v[148:151], v126 offset:6400
	v_add_f32_dpp v58, v58, v58 quad_perm:[1,0,3,2] row_mask:0xf bank_mask:0xf bound_ctrl:1
	v_add_f32_e32 v42, v68, v69
	ds_read_b128 v[152:155], v126 offset:10496
	v_add_f32_dpp v58, v58, v58 quad_perm:[2,3,0,1] row_mask:0xf bank_mask:0xf bound_ctrl:1
	v_pk_mul_f32 v[64:65], v[176:177], v[184:185] op_sel:[0,1] op_sel_hi:[1,1]
	ds_read_b128 v[156:159], v126 offset:14592
	v_add_f32_dpp v58, v58, v58 row_half_mirror row_mask:0xf bank_mask:0xf bound_ctrl:1
	v_pk_mul_f32 v[66:67], v[178:179], v[184:185] op_sel:[0,1] op_sel_hi:[1,1]
	ds_read_b128 v[160:163], v126 offset:18688
	v_add_f32_dpp v58, v58, v58 row_mirror row_mask:0xf bank_mask:0xf bound_ctrl:1
	v_pk_fma_f32 v[64:65], v[172:173], v[58:59], v[64:65] op_sel_hi:[1,0,1] neg_lo:[1,0,0] neg_hi:[1,0,0]
	v_pk_fma_f32 v[66:67], v[174:175], v[58:59], v[66:67] op_sel_hi:[1,0,1] neg_lo:[1,0,0] neg_hi:[1,0,0]
	v_pk_fma_f32 v[32:33], v[32:33], v[164:165], v[64:65]
	v_pk_fma_f32 v[34:35], v[34:35], v[166:167], v[66:67]
	s_waitcnt lgkmcnt(5)
; __device__ __forceinline__ void rwkv_scan_job(const P& p, int job, char* smc) {
;     ...
;     for (int t = 0; t < RW_TC; t++) {
;       if (t + 2 < RW_TC) RW_LD((t + 2) % 3, t + 2);
;       const float4 dec = o_dec[t % 3], kk = o_kk[t % 3], kka = o_kka[t % 3], kp = o_kp[t % 3], wr = o_wr[t % 3];
;       const float vi = o_vi[t % 3], c1 = o_c[t % 3].x, c2 = o_c[t % 3].y;
;       const v2f kk0 = {kk.x, kk.y}, kk1 = {kk.z, kk.w}, wr0 = {wr.x, wr.y}, wr1 = {wr.z, wr.w};
;       v2f ps = Sa * kk0 + Sb * kk1;
;       v2f py = Sa * wr0 + Sb * wr1;
;       float sa = ps.x + ps.y, yd = py.x + py.y;
;       sa = sum16(sa);
;       yv[t] = yd + m0 * (vi * c2 - sa * c1);
;       const v2f dec0 = {dec.x, dec.y}, dec1 = {dec.z, dec.w}, ka0 = {kka.x, kka.y}, ka1 = {kka.z, kka.w},
;                 kp0 = {kp.x, kp.y}, kp1 = {kp.z, kp.w};
;       const v2f sav = {sa, sa}, viv = {vi, vi};
;       Sa = Sa * dec0 - sav * ka0 + viv * kp0;
;       Sb = Sb * dec1 - sav * ka1 + viv * kp1;
;     }
	v_pk_mul_f32 v[52:53], v[32:33], v[236:237]
	v_pk_mul_f32 v[70:71], v[34:35], v[182:183]
	v_pk_fma_f32 v[52:53], v[34:35], v[238:239], v[52:53]
	ds_read_b128 v[164:167], v126 offset:2560
	v_add_f32_e32 v56, v52, v53
	v_pk_fma_f32 v[70:71], v[32:33], v[180:181], v[70:71]
	ds_read_b128 v[168:171], v126 offset:6656
	v_add_f32_dpp v56, v56, v56 quad_perm:[1,0,3,2] row_mask:0xf bank_mask:0xf bound_ctrl:1
	v_add_f32_e32 v43, v70, v71
	ds_read_b128 v[172:175], v126 offset:10752
	v_add_f32_dpp v56, v56, v56 quad_perm:[2,3,0,1] row_mask:0xf bank_mask:0xf bound_ctrl:1
	v_pk_mul_f32 v[60:61], v[244:245], v[186:187] op_sel_hi:[1,0]
	ds_read_b128 v[176:179], v126 offset:14848
	v_add_f32_dpp v56, v56, v56 row_half_mirror row_mask:0xf bank_mask:0xf bound_ctrl:1
	v_pk_mul_f32 v[62:63], v[246:247], v[186:187] op_sel_hi:[1,0]
	ds_read_b128 v[180:183], v126 offset:18944
	v_add_f32_dpp v56, v56, v56 row_mirror row_mask:0xf bank_mask:0xf bound_ctrl:1
	ds_read2_b32 v[188:189], v128 offset0:160 offset1:176
	v_pk_fma_f32 v[60:61], v[240:241], v[56:57], v[60:61] op_sel_hi:[1,0,1] neg_lo:[1,0,0] neg_hi:[1,0,0]
	v_pk_fma_f32 v[62:63], v[242:243], v[56:57], v[62:63] op_sel_hi:[1,0,1] neg_lo:[1,0,0] neg_hi:[1,0,0]
	v_pk_fma_f32 v[32:33], v[32:33], v[232:233], v[60:61]
	v_pk_fma_f32 v[34:35], v[34:35], v[234:235], v[62:63]
	s_waitcnt lgkmcnt(6)
	v_pk_mul_f32 v[54:55], v[32:33], v[148:149]
	v_pk_mul_f32 v[68:69], v[34:35], v[250:251]
	v_pk_fma_f32 v[54:55], v[34:35], v[150:151], v[54:55]
	ds_read_b128 v[232:235], v126 offset:2816
	v_add_f32_e32 v58, v54, v55
	v_pk_fma_f32 v[68:69], v[32:33], v[248:249], v[68:69]
	ds_read_b128 v[236:239], v126 offset:6912
	v_add_f32_dpp v58, v58, v58 quad_perm:[1,0,3,2] row_mask:0xf bank_mask:0xf bound_ctrl:1
	v_add_f32_e32 v44, v68, v69
	ds_read_b128 v[240:243], v126 offset:11008
	v_add_f32_dpp v58, v58, v58 quad_perm:[2,3,0,1] row_mask:0xf bank_mask:0xf bound_ctrl:1
	v_pk_mul_f32 v[64:65], v[156:157], v[186:187] op_sel:[0,1] op_sel_hi:[1,1]
	ds_read_b128 v[244:247], v126 offset:15104
	v_add_f32_dpp v58, v58, v58 row_half_mirror row_mask:0xf bank_mask:0xf bound_ctrl:1
	v_pk_mul_f32 v[66:67], v[158:159], v[186:187] op_sel:[0,1] op_sel_hi:[1,1]
	ds_read_b128 v[248:251], v126 offset:19200
	v_add_f32_dpp v58, v58, v58 row_mirror row_mask:0xf bank_mask:0xf bound_ctrl:1
	v_pk_fma_f32 v[64:65], v[152:153], v[58:59], v[64:65] op_sel_hi:[1,0,1] neg_lo:[1,0,0] neg_hi:[1,0,0]
	v_pk_fma_f32 v[66:67], v[154:155], v[58:59], v[66:67] op_sel_hi:[1,0,1] neg_lo:[1,0,0] neg_hi:[1,0,0]
	v_pk_fma_f32 v[32:33], v[32:33], v[144:145], v[64:65]
	v_pk_fma_f32 v[34:35], v[34:35], v[146:147], v[66:67]
	s_waitcnt lgkmcnt(5)
	v_pk_mul_f32 v[52:53], v[32:33], v[168:169]
	v_pk_mul_f32 v[70:71], v[34:35], v[162:163]
	v_pk_fma_f32 v[52:53], v[34:35], v[170:171], v[52:53]
	ds_read_b128 v[144:147], v126 offset:3072
	v_add_f32_e32 v56, v52, v53
	v_pk_fma_f32 v[70:71], v[32:33], v[160:161], v[70:71]
	ds_read_b128 v[148:151], v126 offset:7168
	v_add_f32_dpp v56, v56, v56 quad_perm:[1,0,3,2] row_mask:0xf bank_mask:0xf bound_ctrl:1
	v_add_f32_e32 v45, v70, v71
	ds_read_b128 v[152:155], v126 offset:11264
	v_add_f32_dpp v56, v56, v56 quad_perm:[2,3,0,1] row_mask:0xf bank_mask:0xf bound_ctrl:1
	v_pk_mul_f32 v[60:61], v[176:177], v[188:189] op_sel_hi:[1,0]
	ds_read_b128 v[156:159], v126 offset:15360
	v_add_f32_dpp v56, v56, v56 row_half_mirror row_mask:0xf bank_mask:0xf bound_ctrl:1
	v_pk_mul_f32 v[62:63], v[178:179], v[188:189] op_sel_hi:[1,0]
	ds_read_b128 v[160:163], v126 offset:19456
	v_add_f32_dpp v56, v56, v56 row_mirror row_mask:0xf bank_mask:0xf bound_ctrl:1
	ds_read2_b32 v[184:185], v128 offset0:192 offset1:208
	v_pk_fma_f32 v[60:61], v[172:173], v[56:57], v[60:61] op_sel_hi:[1,0,1] neg_lo:[1,0,0] neg_hi:[1,0,0]
	v_pk_fma_f32 v[62:63], v[174:175], v[56:57], v[62:63] op_sel_hi:[1,0,1] neg_lo:[1,0,0] neg_hi:[1,0,0]
	v_pk_fma_f32 v[32:33], v[32:33], v[164:165], v[60:61]
	v_pk_fma_f32 v[34:35], v[34:35], v[166:167], v[62:63]
	s_waitcnt lgkmcnt(6)
	v_pk_mul_f32 v[54:55], v[32:33], v[236:237]
	v_pk_mul_f32 v[68:69], v[34:35], v[182:183]
	v_pk_fma_f32 v[54:55], v[34:35], v[238:239], v[54:55]
	ds_read_b128 v[164:167], v126 offset:3328
	v_add_f32_e32 v58, v54, v55
	v_pk_fma_f32 v[68:69], v[32:33], v[180:181], v[68:69]
	ds_read_b128 v[168:171], v126 offset:7424
	v_add_f32_dpp v58, v58, v58 quad_perm:[1,0,3,2] row_mask:0xf bank_mask:0xf bound_ctrl:1
	v_add_f32_e32 v46, v68, v69
	ds_read_b128 v[172:175], v126 offset:11520
	v_add_f32_dpp v58, v58, v58 quad_perm:[2,3,0,1] row_mask:0xf bank_mask:0xf bound_ctrl:1
	v_pk_mul_f32 v[64:65], v[244:245], v[188:189] op_sel:[0,1] op_sel_hi:[1,1]
	ds_read_b128 v[176:179], v126 offset:15616
	v_add_f32_dpp v58, v58, v58 row_half_mirror row_mask:0xf bank_mask:0xf bound_ctrl:1
	v_pk_mul_f32 v[66:67], v[246:247], v[188:189] op_sel:[0,1] op_sel_hi:[1,1]
	ds_read_b128 v[180:183], v126 offset:19712
	v_add_f32_dpp v58, v58, v58 row_mirror row_mask:0xf bank_mask:0xf bound_ctrl:1
	v_pk_fma_f32 v[64:65], v[240:241], v[58:59], v[64:65] op_sel_hi:[1,0,1] neg_lo:[1,0,0] neg_hi:[1,0,0]
	v_pk_fma_f32 v[66:67], v[242:243], v[58:59], v[66:67] op_sel_hi:[1,0,1] neg_lo:[1,0,0] neg_hi:[1,0,0]
	v_pk_fma_f32 v[32:33], v[32:33], v[232:233], v[64:65]
	v_pk_fma_f32 v[34:35], v[34:35], v[234:235], v[66:67]
	s_waitcnt lgkmcnt(5)
; __device__ __forceinline__ void rwkv_scan_job(const P& p, int job, char* smc) {
;     ...
;     for (int t = 0; t < RW_TC; t++) {
;       if (t + 2 < RW_TC) RW_LD((t + 2) % 3, t + 2);
;       const float4 dec = o_dec[t % 3], kk = o_kk[t % 3], kka = o_kka[t % 3], kp = o_kp[t % 3], wr = o_wr[t % 3];
;       const float vi = o_vi[t % 3], c1 = o_c[t % 3].x, c2 = o_c[t % 3].y;
;       const v2f kk0 = {kk.x, kk.y}, kk1 = {kk.z, kk.w}, wr0 = {wr.x, wr.y}, wr1 = {wr.z, wr.w};
;       v2f ps = Sa * kk0 + Sb * kk1;
;       v2f py = Sa * wr0 + Sb * wr1;
;       float sa = ps.x + ps.y, yd = py.x + py.y;
;       sa = sum16(sa);
;       yv[t] = yd + m0 * (vi * c2 - sa * c1);
;       const v2f dec0 = {dec.x, dec.y}, dec1 = {dec.z, dec.w}, ka0 = {kka.x, kka.y}, ka1 = {kka.z, kka.w},
;                 kp0 = {kp.x, kp.y}, kp1 = {kp.z, kp.w};
;       const v2f sav = {sa, sa}, viv = {vi, vi};
;       Sa = Sa * dec0 - sav * ka0 + viv * kp0;
;       Sb = Sb * dec1 - sav * ka1 + viv * kp1;
;     }
	v_pk_mul_f32 v[52:53], v[32:33], v[148:149]
	v_pk_mul_f32 v[70:71], v[34:35], v[250:251]
	v_pk_fma_f32 v[52:53], v[34:35], v[150:151], v[52:53]
	ds_read_b128 v[232:235], v126 offset:3584
	v_add_f32_e32 v56, v52, v53
	v_pk_fma_f32 v[70:71], v[32:33], v[248:249], v[70:71]
	ds_read_b128 v[236:239], v126 offset:7680
	v_add_f32_dpp v56, v56, v56 quad_perm:[1,0,3,2] row_mask:0xf bank_mask:0xf bound_ctrl:1
	v_add_f32_e32 v47, v70, v71
	ds_read_b128 v[240:243], v126 offset:11776
	v_add_f32_dpp v56, v56, v56 quad_perm:[2,3,0,1] row_mask:0xf bank_mask:0xf bound_ctrl:1
	v_pk_mul_f32 v[60:61], v[156:157], v[184:185] op_sel_hi:[1,0]
	ds_read_b128 v[244:247], v126 offset:15872
	v_add_f32_dpp v56, v56, v56 row_half_mirror row_mask:0xf bank_mask:0xf bound_ctrl:1
	v_pk_mul_f32 v[62:63], v[158:159], v[184:185] op_sel_hi:[1,0]
	ds_read_b128 v[248:251], v126 offset:19968
	v_add_f32_dpp v56, v56, v56 row_mirror row_mask:0xf bank_mask:0xf bound_ctrl:1
	ds_read2_b32 v[186:187], v128 offset0:224 offset1:240
	v_pk_fma_f32 v[60:61], v[152:153], v[56:57], v[60:61] op_sel_hi:[1,0,1] neg_lo:[1,0,0] neg_hi:[1,0,0]
	v_pk_fma_f32 v[62:63], v[154:155], v[56:57], v[62:63] op_sel_hi:[1,0,1] neg_lo:[1,0,0] neg_hi:[1,0,0]
	v_pk_fma_f32 v[32:33], v[32:33], v[144:145], v[60:61]
	v_pk_fma_f32 v[34:35], v[34:35], v[146:147], v[62:63]
	s_waitcnt lgkmcnt(6)
	v_pk_mul_f32 v[54:55], v[32:33], v[168:169]
	v_pk_mul_f32 v[68:69], v[34:35], v[162:163]
	v_pk_fma_f32 v[54:55], v[34:35], v[170:171], v[54:55]
	ds_read_b128 v[144:147], v126 offset:3840
	v_add_f32_e32 v58, v54, v55
	v_pk_fma_f32 v[68:69], v[32:33], v[160:161], v[68:69]
	ds_read_b128 v[148:151], v126 offset:7936
	v_add_f32_dpp v58, v58, v58 quad_perm:[1,0,3,2] row_mask:0xf bank_mask:0xf bound_ctrl:1
	v_add_f32_e32 v48, v68, v69
	ds_read_b128 v[152:155], v126 offset:12032
	v_add_f32_dpp v58, v58, v58 quad_perm:[2,3,0,1] row_mask:0xf bank_mask:0xf bound_ctrl:1
	v_pk_mul_f32 v[64:65], v[176:177], v[184:185] op_sel:[0,1] op_sel_hi:[1,1]
	ds_read_b128 v[156:159], v126 offset:16128
	v_add_f32_dpp v58, v58, v58 row_half_mirror row_mask:0xf bank_mask:0xf bound_ctrl:1
	v_pk_mul_f32 v[66:67], v[178:179], v[184:185] op_sel:[0,1] op_sel_hi:[1,1]
	ds_read_b128 v[160:163], v126 offset:20224
	v_add_f32_dpp v58, v58, v58 row_mirror row_mask:0xf bank_mask:0xf bound_ctrl:1
	v_pk_fma_f32 v[64:65], v[172:173], v[58:59], v[64:65] op_sel_hi:[1,0,1] neg_lo:[1,0,0] neg_hi:[1,0,0]
	v_pk_fma_f32 v[66:67], v[174:175], v[58:59], v[66:67] op_sel_hi:[1,0,1] neg_lo:[1,0,0] neg_hi:[1,0,0]
	v_pk_fma_f32 v[32:33], v[32:33], v[164:165], v[64:65]
	v_pk_fma_f32 v[34:35], v[34:35], v[166:167], v[66:67]
	s_waitcnt lgkmcnt(5)
	v_pk_mul_f32 v[52:53], v[32:33], v[236:237]
	v_pk_mul_f32 v[70:71], v[34:35], v[182:183]
	v_pk_fma_f32 v[52:53], v[34:35], v[238:239], v[52:53]
	v_pk_mul_f32 v[60:61], v[244:245], v[186:187] op_sel_hi:[1,0]
	v_add_f32_e32 v56, v52, v53
	v_pk_fma_f32 v[70:71], v[32:33], v[180:181], v[70:71]
	v_pk_mul_f32 v[62:63], v[246:247], v[186:187] op_sel_hi:[1,0]
	v_add_f32_dpp v56, v56, v56 quad_perm:[1,0,3,2] row_mask:0xf bank_mask:0xf bound_ctrl:1
	v_add_f32_e32 v49, v70, v71
	s_nop 0
	v_add_f32_dpp v56, v56, v56 quad_perm:[2,3,0,1] row_mask:0xf bank_mask:0xf bound_ctrl:1
	s_nop 0
	s_nop 0
	v_add_f32_dpp v56, v56, v56 row_half_mirror row_mask:0xf bank_mask:0xf bound_ctrl:1
	s_nop 0
	s_nop 0
	v_add_f32_dpp v56, v56, v56 row_mirror row_mask:0xf bank_mask:0xf bound_ctrl:1
	v_pk_fma_f32 v[60:61], v[240:241], v[56:57], v[60:61] op_sel_hi:[1,0,1] neg_lo:[1,0,0] neg_hi:[1,0,0]
	v_pk_fma_f32 v[62:63], v[242:243], v[56:57], v[62:63] op_sel_hi:[1,0,1] neg_lo:[1,0,0] neg_hi:[1,0,0]
	v_pk_fma_f32 v[32:33], v[32:33], v[232:233], v[60:61]
	v_pk_fma_f32 v[34:35], v[34:35], v[234:235], v[62:63]
	s_waitcnt lgkmcnt(0)
; __device__ __forceinline__ void rwkv_scan_job(const P& p, int job, char* smc) {
;     ...
;     for (int t = 0; t < RW_TC; t++) {
;       if (t + 2 < RW_TC) RW_LD((t + 2) % 3, t + 2);
;       const float4 dec = o_dec[t % 3], kk = o_kk[t % 3], kka = o_kka[t % 3], kp = o_kp[t % 3], wr = o_wr[t % 3];
;       const float vi = o_vi[t % 3], c1 = o_c[t % 3].x, c2 = o_c[t % 3].y;
;       const v2f kk0 = {kk.x, kk.y}, kk1 = {kk.z, kk.w}, wr0 = {wr.x, wr.y}, wr1 = {wr.z, wr.w};
;       v2f ps = Sa * kk0 + Sb * kk1;
;       v2f py = Sa * wr0 + Sb * wr1;
;       float sa = ps.x + ps.y, yd = py.x + py.y;
;       sa = sum16(sa);
;       yv[t] = yd + m0 * (vi * c2 - sa * c1);
;       const v2f dec0 = {dec.x, dec.y}, dec1 = {dec.z, dec.w}, ka0 = {kka.x, kka.y}, ka1 = {kka.z, kka.w},
;                 kp0 = {kp.x, kp.y}, kp1 = {kp.z, kp.w};
;       const v2f sav = {sa, sa}, viv = {vi, vi};
;       Sa = Sa * dec0 - sav * ka0 + viv * kp0;
;       Sb = Sb * dec1 - sav * ka1 + viv * kp1;
;     }
;     ...
;     {
;       float r8[8], r4[4], r2[2];
; #pragma unroll
;       for (int i = 0; i < 8; i++) {
;         const float keep = b3 ? yv[i + 8] : yv[i], send = b3 ? yv[i] : yv[i + 8];
;         r8[i] = keep + dppf<0x128>(send);
;       }
; #pragma unroll
;       for (int i = 0; i < 4; i++) {
;         const float keep = b2 ? r8[i + 4] : r8[i], send = b2 ? r8[i] : r8[i + 4];
;         r4[i] = keep + dppf<0x141>(send);
;       }
; #pragma unroll
;       for (int i = 0; i < 2; i++) {
;         const float keep = b1 ? r4[i + 2] : r4[i], send = b1 ? r4[i] : r4[i + 2];
;         r2[i] = keep + dppf<0x4E>(send);
;       }
;       const float keep = b0 ? r2[1] : r2[0], send = b0 ? r2[0] : r2[1];
;       const float ysum = keep + dppf<0xB1>(send);
;       yb[(lane & 15) * 16 + il] = ysum;
;     }
;     if (more) stage(bufs[(c + 1) & 1]);
	v_pk_mul_f32 v[54:55], v[32:33], v[148:149]
	v_pk_mul_f32 v[68:69], v[34:35], v[250:251]
	v_pk_fma_f32 v[54:55], v[34:35], v[150:151], v[54:55]
	v_pk_mul_f32 v[64:65], v[156:157], v[186:187] op_sel:[0,1] op_sel_hi:[1,1]
	v_add_f32_e32 v58, v54, v55
	v_pk_fma_f32 v[68:69], v[32:33], v[248:249], v[68:69]
	v_pk_mul_f32 v[66:67], v[158:159], v[186:187] op_sel:[0,1] op_sel_hi:[1,1]
	v_add_f32_dpp v58, v58, v58 quad_perm:[1,0,3,2] row_mask:0xf bank_mask:0xf bound_ctrl:1
	v_add_f32_e32 v50, v68, v69
	s_nop 0
	v_add_f32_dpp v58, v58, v58 quad_perm:[2,3,0,1] row_mask:0xf bank_mask:0xf bound_ctrl:1
	s_nop 0
	s_nop 0
	v_add_f32_dpp v58, v58, v58 row_half_mirror row_mask:0xf bank_mask:0xf bound_ctrl:1
	s_nop 0
	s_nop 0
	v_add_f32_dpp v58, v58, v58 row_mirror row_mask:0xf bank_mask:0xf bound_ctrl:1
	v_pk_fma_f32 v[64:65], v[152:153], v[58:59], v[64:65] op_sel_hi:[1,0,1] neg_lo:[1,0,0] neg_hi:[1,0,0]
	v_pk_fma_f32 v[66:67], v[154:155], v[58:59], v[66:67] op_sel_hi:[1,0,1] neg_lo:[1,0,0] neg_hi:[1,0,0]
	v_pk_fma_f32 v[32:33], v[32:33], v[144:145], v[64:65]
	v_pk_fma_f32 v[34:35], v[34:35], v[146:147], v[66:67]
	s_nop 0
	v_pk_mul_f32 v[70:71], v[34:35], v[162:163]
	s_nop 0
	v_pk_fma_f32 v[70:71], v[32:33], v[160:161], v[70:71]
	s_nop 0
	v_add_f32_e32 v51, v70, v71
	v_cndmask_b32_e64 v104, v44, v36, s[10:11]
	v_cndmask_b32_e64 v105, v36, v44, s[10:11]
	v_cndmask_b32_e64 v106, v45, v37, s[10:11]
	v_cndmask_b32_e64 v107, v37, v45, s[10:11]
	v_cndmask_b32_e64 v108, v46, v38, s[10:11]
	v_cndmask_b32_e64 v109, v38, v46, s[10:11]
	v_cndmask_b32_e64 v110, v47, v39, s[10:11]
	v_cndmask_b32_e64 v111, v39, v47, s[10:11]
	v_cndmask_b32_e64 v24, v48, v40, s[10:11]
	v_cndmask_b32_e64 v25, v40, v48, s[10:11]
	v_cndmask_b32_e64 v26, v49, v41, s[10:11]
	v_cndmask_b32_e64 v27, v41, v49, s[10:11]
	v_cndmask_b32_e64 v28, v50, v42, s[10:11]
	v_cndmask_b32_e64 v29, v42, v50, s[10:11]
	v_cndmask_b32_e64 v30, v51, v43, s[10:11]
	v_cndmask_b32_e64 v31, v43, v51, s[10:11]
	v_add_f32_dpp v36, v105, v104 row_ror:8 row_mask:0xf bank_mask:0xf bound_ctrl:1
	v_add_f32_dpp v37, v107, v106 row_ror:8 row_mask:0xf bank_mask:0xf bound_ctrl:1
	v_add_f32_dpp v38, v109, v108 row_ror:8 row_mask:0xf bank_mask:0xf bound_ctrl:1
	v_add_f32_dpp v39, v111, v110 row_ror:8 row_mask:0xf bank_mask:0xf bound_ctrl:1
	v_add_f32_dpp v40, v25, v24 row_ror:8 row_mask:0xf bank_mask:0xf bound_ctrl:1
	v_add_f32_dpp v41, v27, v26 row_ror:8 row_mask:0xf bank_mask:0xf bound_ctrl:1
	v_add_f32_dpp v42, v29, v28 row_ror:8 row_mask:0xf bank_mask:0xf bound_ctrl:1
	v_add_f32_dpp v43, v31, v30 row_ror:8 row_mask:0xf bank_mask:0xf bound_ctrl:1
	v_cndmask_b32_e64 v104, v40, v36, s[12:13]
	v_cndmask_b32_e64 v105, v36, v40, s[12:13]
	v_cndmask_b32_e64 v106, v41, v37, s[12:13]
	v_cndmask_b32_e64 v107, v37, v41, s[12:13]
	v_cndmask_b32_e64 v108, v42, v38, s[12:13]
	v_cndmask_b32_e64 v109, v38, v42, s[12:13]
	v_cndmask_b32_e64 v110, v43, v39, s[12:13]
	v_cndmask_b32_e64 v111, v39, v43, s[12:13]
	v_add_f32_dpp v36, v105, v104 row_half_mirror row_mask:0xf bank_mask:0xf bound_ctrl:1
	v_add_f32_dpp v37, v107, v106 row_half_mirror row_mask:0xf bank_mask:0xf bound_ctrl:1
	v_add_f32_dpp v38, v109, v108 row_half_mirror row_mask:0xf bank_mask:0xf bound_ctrl:1
	v_add_f32_dpp v39, v111, v110 row_half_mirror row_mask:0xf bank_mask:0xf bound_ctrl:1
	v_cndmask_b32_e64 v104, v38, v36, s[14:15]
	v_cndmask_b32_e64 v105, v36, v38, s[14:15]
	v_cndmask_b32_e64 v106, v39, v37, s[14:15]
	v_cndmask_b32_e64 v107, v37, v39, s[14:15]
	s_nop 1
	v_add_f32_dpp v36, v105, v104 quad_perm:[2,3,0,1] row_mask:0xf bank_mask:0xf bound_ctrl:1
	v_add_f32_dpp v37, v107, v106 quad_perm:[2,3,0,1] row_mask:0xf bank_mask:0xf bound_ctrl:1
	v_cndmask_b32_e64 v104, v37, v36, s[16:17]
	v_cndmask_b32_e64 v105, v36, v37, s[16:17]
	s_nop 1
	v_add_f32_dpp v36, v105, v104 quad_perm:[1,0,3,2] row_mask:0xf bank_mask:0xf bound_ctrl:1
	v_or_b32_e32 v24, s61, v119
	v_add_u32_e32 v24, v24, v97
	s_andn2_b64 vcc, exec, s[6:7]
	ds_write_b32 v24, v36 offset:43264
	s_cbranch_vccnz .LBB0_161
	s_waitcnt vmcnt(4)
	v_lshlrev_b32_e32 v42, 16, v80
	v_and_b32_e32 v43, 0xffff0000, v80
	v_lshlrev_b32_e32 v40, 16, v81
	v_and_b32_e32 v41, 0xffff0000, v81
	s_waitcnt vmcnt(3)
	v_lshlrev_b32_e32 v50, 16, v86
	v_and_b32_e32 v51, 0xffff0000, v86
	v_lshlrev_b32_e32 v52, 16, v87
	v_and_b32_e32 v53, 0xffff0000, v87
	s_waitcnt vmcnt(2)
	v_lshlrev_b32_e32 v36, 16, v88
	v_and_b32_e32 v37, 0xffff0000, v88
	v_lshlrev_b32_e32 v38, 16, v89
	v_and_b32_e32 v39, 0xffff0000, v89
	s_and_saveexec_b64 s[6:7], s[94:95]
	s_cbranch_execz .LBB0_167
	v_mov_b32_e32 v50, 0
	v_mov_b32_e32 v51, v50
	v_mov_b32_e32 v52, v50
	v_mov_b32_e32 v53, v50
	v_mov_b32_e32 v42, v50
	v_mov_b32_e32 v43, v50
	v_mov_b32_e32 v40, v50
	v_mov_b32_e32 v41, v50
	v_mov_b32_e32 v36, v50
	v_mov_b32_e32 v37, v50
	v_mov_b32_e32 v38, v50
	v_mov_b32_e32 v39, v50

; template <class F>
; __device__ __forceinline__ void gemm_big(const ALbf& al, const u16* __restrict__ Wt, int K, int m0, int n0, const F& f, u16* sm) {
;     ...
; #pragma unroll
;   for (int pq = 0; pq < 2; pq++)
; #pragma unroll
;     for (int j = 0; j < 8; j++)
;       f(m0 + wm * 128 + j * 16 + (lane & 15), n0 + wn * 64 + pq * 32 + (lane >> 4) * 8, acc[2 * pq][j], acc[2 * pq + 1][j]);
; }
; __device__ __forceinline__ uint4 pack8v(const f32x4& a, const f32x4& b) {
;   return make_uint4(pack2(a[0], a[1]), pack2(a[2], a[3]), pack2(b[0], b[1]), pack2(b[2], b[3]));
; }
; __global__ void __launch_bounds__(NTHR, 2) mega(P p, int ph_lo, int ph_hi) {
;     ...
;         auto f8 = [=] __device__(int m, int n, const f32x4& a, const f32x4& b) { *(uint4*)((u16*)p.H + (size_t)m * PROJ1_LD + n) = pack8v(a, b); };
;         gemm_big_jobs(ALbf{p.A, 1024}, p.Win1, 1024, 22, f8, smu, bid, nb);
.LBB0_193:
	v_and_b32_e32 v129, 0xffffff80, v138
	v_add_u32_e32 v129, s15, v129
	v_and_b32_e32 v128, 64, v138
	v_and_or_b32 v130, v138, 15, v129
	v_lshlrev_b32_e32 v129, 3, v140
	v_or3_b32 v128, v129, v128, s14
	v_ashrrev_i32_e32 v129, 31, v128
	v_cvt_pk_bf16_f32 v124, v124, v125
	v_cvt_pk_bf16_f32 v125, v126, v127
	v_cvt_pk_bf16_f32 v126, v120, v121
	v_mov_b64_e32 v[120:121], s[22:23]
	v_cvt_pk_bf16_f32 v127, v122, v123
	v_mad_i64_i32 v[122:123], s[6:7], v130, s56, v[120:121]
	v_lshlrev_b64 v[128:129], 1, v[128:129]
	v_lshl_add_u64 v[122:123], v[122:123], 0, v[128:129]
	v_cvt_pk_bf16_f32 v52, v52, v53
	v_cvt_pk_bf16_f32 v53, v54, v55
	v_cvt_pk_bf16_f32 v55, v50, v51
	v_or_b32_e32 v50, 0x70, v130
	global_store_dwordx4 v[122:123], v[124:127], off sc1
	v_cvt_pk_bf16_f32 v36, v36, v37
	v_cvt_pk_bf16_f32 v37, v38, v39
	v_or_b32_e32 v124, 16, v130
	v_cvt_pk_bf16_f32 v38, v32, v33
	v_mad_i64_i32 v[32:33], s[6:7], v50, s56, v[120:121]
	v_cvt_pk_bf16_f32 v116, v116, v117
	v_cvt_pk_bf16_f32 v117, v118, v119
	v_cvt_pk_bf16_f32 v118, v112, v113
	v_cvt_pk_bf16_f32 v119, v114, v115
	v_mad_i64_i32 v[112:113], s[6:7], v124, s56, v[120:121]
	v_or_b32_e32 v114, 32, v130
	v_cvt_pk_bf16_f32 v39, v34, v35
	v_lshl_add_u64 v[50:51], v[32:33], 0, v[128:129]
	v_cvt_pk_bf16_f32 v32, v92, v93
	v_cvt_pk_bf16_f32 v33, v94, v95
	v_cvt_pk_bf16_f32 v34, v88, v89
	v_cvt_pk_bf16_f32 v35, v90, v91
	v_lshl_add_u64 v[112:113], v[112:113], 0, v[128:129]
	v_cvt_pk_bf16_f32 v108, v108, v109
	v_cvt_pk_bf16_f32 v109, v110, v111
	v_cvt_pk_bf16_f32 v110, v104, v105
	v_cvt_pk_bf16_f32 v111, v106, v107
	v_mad_i64_i32 v[104:105], s[6:7], v114, s56, v[120:121]
	v_or_b32_e32 v106, 48, v130
	v_cvt_pk_bf16_f32 v100, v100, v101
	v_cvt_pk_bf16_f32 v101, v102, v103
	v_cvt_pk_bf16_f32 v103, v98, v99
	v_or_b32_e32 v98, 64, v130
	v_cvt_pk_bf16_f32 v84, v84, v85
	v_cvt_pk_bf16_f32 v85, v86, v87
	v_cvt_pk_bf16_f32 v87, v82, v83
	v_or_b32_e32 v82, 0x50, v130
	v_cvt_pk_bf16_f32 v68, v68, v69
	v_cvt_pk_bf16_f32 v69, v70, v71
	v_cvt_pk_bf16_f32 v71, v66, v67
	v_or_b32_e32 v66, 0x60, v130
	global_store_dwordx4 v[122:123], v[32:35], off offset:64 sc1
	v_lshl_add_u64 v[104:105], v[104:105], 0, v[128:129]
	v_cvt_pk_bf16_f32 v102, v96, v97
	v_cvt_pk_bf16_f32 v32, v76, v77
	v_cvt_pk_bf16_f32 v33, v78, v79
	v_cvt_pk_bf16_f32 v34, v72, v73
	v_cvt_pk_bf16_f32 v35, v74, v75
	v_mad_i64_i32 v[96:97], s[6:7], v106, s56, v[120:121]
	v_cvt_pk_bf16_f32 v86, v80, v81
	v_mad_i64_i32 v[80:81], s[6:7], v98, s56, v[120:121]
	v_cvt_pk_bf16_f32 v70, v64, v65
	v_mad_i64_i32 v[64:65], s[6:7], v82, s56, v[120:121]
	v_cvt_pk_bf16_f32 v54, v48, v49
	v_mad_i64_i32 v[48:49], s[6:7], v66, s56, v[120:121]
	global_store_dwordx4 v[112:113], v[32:35], off offset:64 sc1
	s_add_i32 s13, s13, s82
	s_add_i32 s4, s4, s33
	v_cvt_pk_bf16_f32 v32, v60, v61
	v_cvt_pk_bf16_f32 v33, v62, v63
	v_cvt_pk_bf16_f32 v34, v56, v57
	v_cvt_pk_bf16_f32 v35, v58, v59
	s_add_i32 s12, s12, s81
	v_lshl_add_u64 v[96:97], v[96:97], 0, v[128:129]
	v_lshl_add_u64 v[80:81], v[80:81], 0, v[128:129]
	v_lshl_add_u64 v[64:65], v[64:65], 0, v[128:129]
	v_lshl_add_u64 v[48:49], v[48:49], 0, v[128:129]
	global_store_dwordx4 v[104:105], v[32:35], off offset:64 sc1
	v_cvt_pk_bf16_f32 v28, v28, v29
	v_cvt_pk_bf16_f32 v29, v30, v31
	v_cvt_pk_bf16_f32 v32, v44, v45
	v_cvt_pk_bf16_f32 v33, v46, v47
	v_cvt_pk_bf16_f32 v34, v40, v41
	v_cvt_pk_bf16_f32 v35, v42, v43
	v_cvt_pk_bf16_f32 v30, v24, v25
	v_cvt_pk_bf16_f32 v31, v26, v27
	v_cvt_pk_bf16_f32 v20, v20, v21
	v_cvt_pk_bf16_f32 v21, v22, v23
	v_cvt_pk_bf16_f32 v22, v16, v17
	v_cvt_pk_bf16_f32 v23, v18, v19
	v_cvt_pk_bf16_f32 v12, v12, v13
	v_cvt_pk_bf16_f32 v13, v14, v15
	v_cvt_pk_bf16_f32 v14, v8, v9
	v_cvt_pk_bf16_f32 v15, v10, v11
	v_cvt_pk_bf16_f32 v4, v4, v5
	v_cvt_pk_bf16_f32 v5, v6, v7
	v_cvt_pk_bf16_f32 v6, v0, v1
	v_cvt_pk_bf16_f32 v7, v2, v3
	s_cmpk_gt_i32 s13, 0x57f
	global_store_dwordx4 v[112:113], v[116:119], off sc1
	global_store_dwordx4 v[104:105], v[108:111], off sc1
	global_store_dwordx4 v[96:97], v[100:103], off sc1
	global_store_dwordx4 v[80:81], v[84:87], off sc1
	global_store_dwordx4 v[64:65], v[68:71], off sc1
	global_store_dwordx4 v[48:49], v[52:55], off sc1
	global_store_dwordx4 v[50:51], v[36:39], off sc1
	global_store_dwordx4 v[96:97], v[32:35], off offset:64 sc1
	global_store_dwordx4 v[80:81], v[28:31], off offset:64 sc1
	global_store_dwordx4 v[64:65], v[20:23], off offset:64 sc1
	global_store_dwordx4 v[48:49], v[12:15], off offset:64 sc1
	global_store_dwordx4 v[50:51], v[4:7], off offset:64 sc1
	s_cbranch_scc1 .LBB0_202

; template <class F>
; __device__ __forceinline__ void gemm_big(const ALbf& al, const u16* __restrict__ Wt, int K, int m0, int n0, const F& f, u16* sm) {
;     ...
; #pragma unroll
;   for (int pq = 0; pq < 2; pq++)
; #pragma unroll
;     for (int j = 0; j < 8; j++)
;       f(m0 + wm * 128 + j * 16 + (lane & 15), n0 + wn * 64 + pq * 32 + (lane >> 4) * 8, acc[2 * pq][j], acc[2 * pq + 1][j]);
; __global__ void __launch_bounds__(NTHR, 2) mega(P p, int ph_lo, int ph_hi) {
;     ...
;         auto f8 = [=] __device__(int m, int n, const f32x4& a, const f32x4& b) {
;           f32x4 ra, rb;
; #pragma unroll
;           for (int q = 0; q < 4; q++) { float x = fmaxf(a[q], 0.f), y = fmaxf(b[q], 0.f); ra[q] = x * x; rb[q] = y * y; }
;           *(uint4*)(hid + (size_t)m * 4096 + n) = pack8v(ra, rb);
;         };
;         gemm_big_jobs(ALbf{p.A, 1024}, p.W1, 1024, 32, f8, smu, bid, nb);
.LBB0_217:
	v_and_b32_e32 v128, 0xffffff80, v138
	v_add_u32_e32 v128, s61, v128
	v_max_f32_e32 v124, v124, v124
	v_max_f32_e32 v120, v120, v120
	v_max_f32_e32 v125, v125, v125
	v_max_f32_e32 v121, v121, v121
	v_max_f32_e32 v126, v126, v126
	v_max_f32_e32 v127, v127, v127
	v_and_b32_e32 v129, 64, v138
	v_and_or_b32 v128, v138, 15, v128
	v_lshlrev_b32_e32 v130, 3, v140
	v_max_f32_e32 v124, 0, v124
	v_max_f32_e32 v120, 0, v120
	v_max_f32_e32 v125, 0, v125
	v_max_f32_e32 v121, 0, v121
	v_max_f32_e32 v126, 0, v126
	v_max_f32_e32 v122, v122, v122
	v_max_f32_e32 v127, 0, v127
	v_max_f32_e32 v123, v123, v123
	v_or3_b32 v130, v130, v129, s60
	v_pk_mul_f32 v[124:125], v[124:125], v[124:125]
	v_pk_mul_f32 v[120:121], v[120:121], v[120:121]
	v_max_f32_e32 v122, 0, v122
	v_max_f32_e32 v123, 0, v123
	v_pk_mul_f32 v[126:127], v[126:127], v[126:127]
	v_ashrrev_i32_e32 v129, 31, v128
	v_ashrrev_i32_e32 v131, 31, v130
	v_pk_mul_f32 v[122:123], v[122:123], v[122:123]
	v_cvt_pk_bf16_f32 v124, v124, v125
	v_cvt_pk_bf16_f32 v125, v126, v127
	v_cvt_pk_bf16_f32 v126, v120, v121
	v_lshlrev_b64 v[120:121], 13, v[128:129]
	v_cvt_pk_bf16_f32 v127, v122, v123
	v_lshl_add_u64 v[120:121], s[22:23], 0, v[120:121]
	v_lshlrev_b64 v[122:123], 1, v[130:131]
	v_lshl_add_u64 v[120:121], v[120:121], 0, v[122:123]
	v_max_f32_e32 v116, v116, v116
	v_max_f32_e32 v112, v112, v112
	v_max_f32_e32 v117, v117, v117
	v_max_f32_e32 v113, v113, v113
	global_store_dwordx4 v[120:121], v[124:127], off sc1
	v_max_f32_e32 v116, 0, v116
	v_max_f32_e32 v112, 0, v112
	v_or_b32_e32 v124, 16, v128
	v_max_f32_e32 v117, 0, v117
	v_max_f32_e32 v113, 0, v113
	v_max_f32_e32 v114, v114, v114
	v_max_f32_e32 v115, v115, v115
	v_pk_mul_f32 v[116:117], v[116:117], v[116:117]
	v_pk_mul_f32 v[112:113], v[112:113], v[112:113]
	v_max_f32_e32 v118, v118, v118
	v_max_f32_e32 v114, 0, v114
	v_max_f32_e32 v119, v119, v119
	v_max_f32_e32 v115, 0, v115
	v_ashrrev_i32_e32 v125, 31, v124
	v_max_f32_e32 v118, 0, v118
	v_max_f32_e32 v119, 0, v119
	v_pk_mul_f32 v[126:127], v[114:115], v[114:115]
	v_cvt_pk_bf16_f32 v114, v116, v117
	v_cvt_pk_bf16_f32 v116, v112, v113
	v_lshlrev_b64 v[112:113], 13, v[124:125]
	v_pk_mul_f32 v[118:119], v[118:119], v[118:119]
	v_lshl_add_u64 v[112:113], s[22:23], 0, v[112:113]
	v_cvt_pk_bf16_f32 v115, v118, v119
	v_cvt_pk_bf16_f32 v117, v126, v127
	v_lshl_add_u64 v[112:113], v[112:113], 0, v[122:123]
	v_max_f32_e32 v108, v108, v108
	v_max_f32_e32 v104, v104, v104
	v_max_f32_e32 v109, v109, v109
	v_max_f32_e32 v105, v105, v105
	global_store_dwordx4 v[112:113], v[114:117], off sc1
	v_max_f32_e32 v108, 0, v108
	v_max_f32_e32 v104, 0, v104
	v_or_b32_e32 v114, 32, v128
	v_max_f32_e32 v109, 0, v109
	v_max_f32_e32 v105, 0, v105
	v_max_f32_e32 v106, v106, v106
	v_max_f32_e32 v107, v107, v107
	v_pk_mul_f32 v[108:109], v[108:109], v[108:109]
	v_pk_mul_f32 v[104:105], v[104:105], v[104:105]
	v_max_f32_e32 v110, v110, v110
	v_max_f32_e32 v106, 0, v106
	v_max_f32_e32 v111, v111, v111
	v_max_f32_e32 v107, 0, v107
	v_ashrrev_i32_e32 v115, 31, v114
	v_max_f32_e32 v110, 0, v110
	v_max_f32_e32 v111, 0, v111
	v_pk_mul_f32 v[116:117], v[106:107], v[106:107]
	v_cvt_pk_bf16_f32 v106, v108, v109
	v_cvt_pk_bf16_f32 v108, v104, v105
	v_lshlrev_b64 v[104:105], 13, v[114:115]
	v_pk_mul_f32 v[110:111], v[110:111], v[110:111]
	v_lshl_add_u64 v[104:105], s[22:23], 0, v[104:105]
	v_cvt_pk_bf16_f32 v107, v110, v111
	v_cvt_pk_bf16_f32 v109, v116, v117
	v_lshl_add_u64 v[104:105], v[104:105], 0, v[122:123]
	v_max_f32_e32 v100, v100, v100
	v_max_f32_e32 v96, v96, v96
	v_max_f32_e32 v101, v101, v101
	v_max_f32_e32 v97, v97, v97
	global_store_dwordx4 v[104:105], v[106:109], off sc1
	v_max_f32_e32 v100, 0, v100
	v_max_f32_e32 v96, 0, v96
	v_or_b32_e32 v106, 48, v128
	v_max_f32_e32 v101, 0, v101
	v_max_f32_e32 v97, 0, v97
	v_max_f32_e32 v98, v98, v98
	v_max_f32_e32 v99, v99, v99
	v_pk_mul_f32 v[100:101], v[100:101], v[100:101]
	v_pk_mul_f32 v[96:97], v[96:97], v[96:97]
	v_max_f32_e32 v102, v102, v102
	v_max_f32_e32 v98, 0, v98
	v_max_f32_e32 v103, v103, v103
	v_max_f32_e32 v99, 0, v99
	v_ashrrev_i32_e32 v107, 31, v106
	v_max_f32_e32 v102, 0, v102
	v_max_f32_e32 v103, 0, v103
	v_pk_mul_f32 v[108:109], v[98:99], v[98:99]
	v_cvt_pk_bf16_f32 v98, v100, v101
	v_cvt_pk_bf16_f32 v100, v96, v97
	v_lshlrev_b64 v[96:97], 13, v[106:107]
	v_pk_mul_f32 v[102:103], v[102:103], v[102:103]
	v_lshl_add_u64 v[96:97], s[22:23], 0, v[96:97]
	v_cvt_pk_bf16_f32 v99, v102, v103
	v_cvt_pk_bf16_f32 v101, v108, v109
	v_lshl_add_u64 v[96:97], v[96:97], 0, v[122:123]
	v_max_f32_e32 v92, v92, v92
	v_max_f32_e32 v88, v88, v88
	v_max_f32_e32 v93, v93, v93
	v_max_f32_e32 v89, v89, v89
	global_store_dwordx4 v[96:97], v[98:101], off sc1
	v_max_f32_e32 v92, 0, v92
	v_max_f32_e32 v88, 0, v88
	v_or_b32_e32 v98, 64, v128
	v_max_f32_e32 v93, 0, v93
	v_max_f32_e32 v89, 0, v89
	v_max_f32_e32 v90, v90, v90
	v_max_f32_e32 v91, v91, v91
	v_pk_mul_f32 v[92:93], v[92:93], v[92:93]
	v_pk_mul_f32 v[88:89], v[88:89], v[88:89]
	v_max_f32_e32 v94, v94, v94
	v_max_f32_e32 v90, 0, v90
	v_max_f32_e32 v95, v95, v95
	v_max_f32_e32 v91, 0, v91
	v_ashrrev_i32_e32 v99, 31, v98
	v_max_f32_e32 v94, 0, v94
	v_max_f32_e32 v95, 0, v95
	v_pk_mul_f32 v[100:101], v[90:91], v[90:91]
	v_cvt_pk_bf16_f32 v90, v92, v93
	v_cvt_pk_bf16_f32 v92, v88, v89
	v_lshlrev_b64 v[88:89], 13, v[98:99]
	v_pk_mul_f32 v[94:95], v[94:95], v[94:95]
	v_lshl_add_u64 v[88:89], s[22:23], 0, v[88:89]
	v_cvt_pk_bf16_f32 v91, v94, v95
	v_cvt_pk_bf16_f32 v93, v100, v101
	v_lshl_add_u64 v[88:89], v[88:89], 0, v[122:123]
	v_max_f32_e32 v84, v84, v84
	v_max_f32_e32 v80, v80, v80
	v_max_f32_e32 v85, v85, v85
	v_max_f32_e32 v81, v81, v81
; template <class F>
; __device__ __forceinline__ void gemm_big(const ALbf& al, const u16* __restrict__ Wt, int K, int m0, int n0, const F& f, u16* sm) {
;     ...
; #pragma unroll
;   for (int pq = 0; pq < 2; pq++)
; #pragma unroll
;     for (int j = 0; j < 8; j++)
;       f(m0 + wm * 128 + j * 16 + (lane & 15), n0 + wn * 64 + pq * 32 + (lane >> 4) * 8, acc[2 * pq][j], acc[2 * pq + 1][j]);
; __global__ void __launch_bounds__(NTHR, 2) mega(P p, int ph_lo, int ph_hi) {
;     ...
;         auto f8 = [=] __device__(int m, int n, const f32x4& a, const f32x4& b) {
;           f32x4 ra, rb;
; #pragma unroll
;           for (int q = 0; q < 4; q++) { float x = fmaxf(a[q], 0.f), y = fmaxf(b[q], 0.f); ra[q] = x * x; rb[q] = y * y; }
;           *(uint4*)(hid + (size_t)m * 4096 + n) = pack8v(ra, rb);
;         };
;         gemm_big_jobs(ALbf{p.A, 1024}, p.W1, 1024, 32, f8, smu, bid, nb);
	global_store_dwordx4 v[88:89], v[90:93], off sc1
	v_max_f32_e32 v84, 0, v84
	v_max_f32_e32 v80, 0, v80
	v_or_b32_e32 v90, 0x50, v128
	v_max_f32_e32 v85, 0, v85
	v_max_f32_e32 v81, 0, v81
	v_max_f32_e32 v82, v82, v82
	v_max_f32_e32 v83, v83, v83
	v_pk_mul_f32 v[84:85], v[84:85], v[84:85]
	v_pk_mul_f32 v[80:81], v[80:81], v[80:81]
	v_max_f32_e32 v86, v86, v86
	v_max_f32_e32 v82, 0, v82
	v_max_f32_e32 v87, v87, v87
	v_max_f32_e32 v83, 0, v83
	v_ashrrev_i32_e32 v91, 31, v90
	v_max_f32_e32 v86, 0, v86
	v_max_f32_e32 v87, 0, v87
	v_pk_mul_f32 v[92:93], v[82:83], v[82:83]
	v_cvt_pk_bf16_f32 v82, v84, v85
	v_cvt_pk_bf16_f32 v84, v80, v81
	v_lshlrev_b64 v[80:81], 13, v[90:91]
	v_pk_mul_f32 v[86:87], v[86:87], v[86:87]
	v_lshl_add_u64 v[80:81], s[22:23], 0, v[80:81]
	v_cvt_pk_bf16_f32 v83, v86, v87
	v_cvt_pk_bf16_f32 v85, v92, v93
	v_lshl_add_u64 v[80:81], v[80:81], 0, v[122:123]
	v_max_f32_e32 v72, v72, v72
	v_max_f32_e32 v64, v64, v64
	v_max_f32_e32 v73, v73, v73
	v_max_f32_e32 v65, v65, v65
	v_max_f32_e32 v74, v74, v74
	v_max_f32_e32 v75, v75, v75
	global_store_dwordx4 v[80:81], v[82:85], off sc1
	v_max_f32_e32 v72, 0, v72
	v_max_f32_e32 v64, 0, v64
	v_or_b32_e32 v82, 0x60, v128
	v_max_f32_e32 v73, 0, v73
	v_max_f32_e32 v65, 0, v65
	v_max_f32_e32 v74, 0, v74
	v_max_f32_e32 v66, v66, v66
	v_max_f32_e32 v75, 0, v75
	v_max_f32_e32 v67, v67, v67
	v_pk_mul_f32 v[72:73], v[72:73], v[72:73]
	v_pk_mul_f32 v[64:65], v[64:65], v[64:65]
	v_max_f32_e32 v66, 0, v66
	v_max_f32_e32 v67, 0, v67
	v_pk_mul_f32 v[74:75], v[74:75], v[74:75]
	v_ashrrev_i32_e32 v83, 31, v82
	v_pk_mul_f32 v[66:67], v[66:67], v[66:67]
	v_cvt_pk_bf16_f32 v72, v72, v73
	v_cvt_pk_bf16_f32 v73, v74, v75
	v_cvt_pk_bf16_f32 v74, v64, v65
	v_lshlrev_b64 v[64:65], 13, v[82:83]
	v_max_f32_e32 v52, v52, v52
	v_max_f32_e32 v48, v48, v48
	v_max_f32_e32 v53, v53, v53
	v_max_f32_e32 v49, v49, v49
	v_cvt_pk_bf16_f32 v75, v66, v67
	v_lshl_add_u64 v[64:65], s[22:23], 0, v[64:65]
	v_or_b32_e32 v66, 0x70, v128
	v_max_f32_e32 v52, 0, v52
	v_max_f32_e32 v48, 0, v48
	v_max_f32_e32 v53, 0, v53
	v_max_f32_e32 v49, 0, v49
	v_max_f32_e32 v50, v50, v50
	v_max_f32_e32 v51, v51, v51
	v_lshl_add_u64 v[64:65], v[64:65], 0, v[122:123]
	v_pk_mul_f32 v[52:53], v[52:53], v[52:53]
	v_pk_mul_f32 v[48:49], v[48:49], v[48:49]
	v_max_f32_e32 v54, v54, v54
	v_max_f32_e32 v50, 0, v50
	v_max_f32_e32 v55, v55, v55
	v_max_f32_e32 v51, 0, v51
	v_ashrrev_i32_e32 v67, 31, v66
	global_store_dwordx4 v[64:65], v[72:75], off sc1
	v_max_f32_e32 v54, 0, v54
	v_max_f32_e32 v55, 0, v55
	v_pk_mul_f32 v[72:73], v[50:51], v[50:51]
	v_cvt_pk_bf16_f32 v50, v52, v53
	v_cvt_pk_bf16_f32 v52, v48, v49
	v_lshlrev_b64 v[48:49], 13, v[66:67]
	v_pk_mul_f32 v[54:55], v[54:55], v[54:55]
	v_lshl_add_u64 v[48:49], s[22:23], 0, v[48:49]
	v_cvt_pk_bf16_f32 v51, v54, v55
	v_cvt_pk_bf16_f32 v53, v72, v73
	v_lshl_add_u64 v[48:49], v[48:49], 0, v[122:123]
	global_store_dwordx4 v[48:49], v[50:53], off sc1
	v_max_f32_e32 v55, v70, v70
	v_max_f32_e32 v54, v78, v78
	v_max_f32_e32 v51, v68, v68
	v_max_f32_e32 v50, v76, v76
	v_max_f32_e32 v52, 0, v51
	v_max_f32_e32 v51, v77, v77
	v_max_f32_e32 v53, v69, v69
	v_max_f32_e32 v66, 0, v55
	v_max_f32_e32 v55, v79, v79
	v_max_f32_e32 v67, v71, v71
	v_max_f32_e32 v50, 0, v50
	v_max_f32_e32 v51, 0, v51
	v_max_f32_e32 v53, 0, v53
	v_max_f32_e32 v54, 0, v54
	v_max_f32_e32 v55, 0, v55
	v_max_f32_e32 v67, 0, v67
	v_pk_mul_f32 v[50:51], v[50:51], v[50:51]
	v_pk_mul_f32 v[52:53], v[52:53], v[52:53]
	v_pk_mul_f32 v[54:55], v[54:55], v[54:55]
	v_pk_mul_f32 v[66:67], v[66:67], v[66:67]
	v_cvt_pk_bf16_f32 v50, v50, v51
	v_cvt_pk_bf16_f32 v51, v54, v55
	v_cvt_pk_bf16_f32 v52, v52, v53
	v_cvt_pk_bf16_f32 v53, v66, v67
	global_store_dwordx4 v[120:121], v[50:53], off offset:64 sc1
	v_max_f32_e32 v55, v58, v58
	v_max_f32_e32 v54, v62, v62
	v_max_f32_e32 v51, v56, v56
	v_max_f32_e32 v50, v60, v60
	v_max_f32_e32 v52, 0, v51
	v_max_f32_e32 v51, v61, v61
	v_max_f32_e32 v53, v57, v57
	v_max_f32_e32 v56, 0, v55
	v_max_f32_e32 v55, v63, v63
	v_max_f32_e32 v57, v59, v59
	v_max_f32_e32 v50, 0, v50
	v_max_f32_e32 v51, 0, v51
	v_max_f32_e32 v53, 0, v53
	v_max_f32_e32 v54, 0, v54
	v_max_f32_e32 v55, 0, v55
	v_max_f32_e32 v57, 0, v57
	v_pk_mul_f32 v[50:51], v[50:51], v[50:51]
	v_pk_mul_f32 v[52:53], v[52:53], v[52:53]
	v_pk_mul_f32 v[54:55], v[54:55], v[54:55]
	v_pk_mul_f32 v[56:57], v[56:57], v[56:57]
	v_max_f32_e32 v40, v40, v40
	v_max_f32_e32 v41, v41, v41
	v_cvt_pk_bf16_f32 v50, v50, v51
	v_cvt_pk_bf16_f32 v51, v54, v55
	v_cvt_pk_bf16_f32 v52, v52, v53
	v_cvt_pk_bf16_f32 v53, v56, v57
	v_max_f32_e32 v40, 0, v40
	v_max_f32_e32 v41, 0, v41
	global_store_dwordx4 v[112:113], v[50:53], off offset:64 sc1
	v_max_f32_e32 v44, v44, v44
	v_max_f32_e32 v45, v45, v45
; template <class F>
; __device__ __forceinline__ void gemm_big(const ALbf& al, const u16* __restrict__ Wt, int K, int m0, int n0, const F& f, u16* sm) {
;     ...
; #pragma unroll
;   for (int pq = 0; pq < 2; pq++)
; #pragma unroll
;     for (int j = 0; j < 8; j++)
;       f(m0 + wm * 128 + j * 16 + (lane & 15), n0 + wn * 64 + pq * 32 + (lane >> 4) * 8, acc[2 * pq][j], acc[2 * pq + 1][j]);
; __global__ void __launch_bounds__(NTHR, 2) mega(P p, int ph_lo, int ph_hi) {
;     ...
;         auto f8 = [=] __device__(int m, int n, const f32x4& a, const f32x4& b) {
;           f32x4 ra, rb;
; #pragma unroll
;           for (int q = 0; q < 4; q++) { float x = fmaxf(a[q], 0.f), y = fmaxf(b[q], 0.f); ra[q] = x * x; rb[q] = y * y; }
;           *(uint4*)(hid + (size_t)m * 4096 + n) = pack8v(ra, rb);
;         };
;         gemm_big_jobs(ALbf{p.A, 1024}, p.W1, 1024, 32, f8, smu, bid, nb);
	v_pk_mul_f32 v[50:51], v[40:41], v[40:41]
	v_max_f32_e32 v41, v42, v42
	v_max_f32_e32 v40, v46, v46
	v_max_f32_e32 v42, 0, v41
	v_max_f32_e32 v41, v47, v47
	v_max_f32_e32 v43, v43, v43
	v_max_f32_e32 v44, 0, v44
	v_max_f32_e32 v45, 0, v45
	v_max_f32_e32 v40, 0, v40
	v_max_f32_e32 v41, 0, v41
	v_max_f32_e32 v43, 0, v43
	v_pk_mul_f32 v[44:45], v[44:45], v[44:45]
	v_pk_mul_f32 v[46:47], v[40:41], v[40:41]
	v_pk_mul_f32 v[52:53], v[42:43], v[42:43]
	v_max_f32_e32 v32, v32, v32
	v_max_f32_e32 v33, v33, v33
	v_cvt_pk_bf16_f32 v40, v44, v45
	v_cvt_pk_bf16_f32 v41, v46, v47
	v_cvt_pk_bf16_f32 v42, v50, v51
	v_cvt_pk_bf16_f32 v43, v52, v53
	v_max_f32_e32 v32, 0, v32
	v_max_f32_e32 v33, 0, v33
	global_store_dwordx4 v[104:105], v[40:43], off offset:64 sc1
	v_max_f32_e32 v36, v36, v36
	v_max_f32_e32 v37, v37, v37
	v_pk_mul_f32 v[40:41], v[32:33], v[32:33]
	v_max_f32_e32 v33, v34, v34
	v_max_f32_e32 v32, v38, v38
	v_max_f32_e32 v34, 0, v33
	v_max_f32_e32 v33, v39, v39
	v_max_f32_e32 v35, v35, v35
	v_max_f32_e32 v36, 0, v36
	v_max_f32_e32 v37, 0, v37
	v_max_f32_e32 v32, 0, v32
	v_max_f32_e32 v33, 0, v33
	v_max_f32_e32 v35, 0, v35
	v_pk_mul_f32 v[36:37], v[36:37], v[36:37]
	v_pk_mul_f32 v[38:39], v[32:33], v[32:33]
	v_pk_mul_f32 v[42:43], v[34:35], v[34:35]
	v_max_f32_e32 v24, v24, v24
	v_max_f32_e32 v25, v25, v25
	v_cvt_pk_bf16_f32 v32, v36, v37
	v_cvt_pk_bf16_f32 v33, v38, v39
	v_cvt_pk_bf16_f32 v34, v40, v41
	v_cvt_pk_bf16_f32 v35, v42, v43
	v_max_f32_e32 v24, 0, v24
	v_max_f32_e32 v25, 0, v25
	global_store_dwordx4 v[96:97], v[32:35], off offset:64 sc1
	v_max_f32_e32 v28, v28, v28
	v_max_f32_e32 v29, v29, v29
	v_pk_mul_f32 v[32:33], v[24:25], v[24:25]
	v_max_f32_e32 v25, v26, v26
	v_max_f32_e32 v24, v30, v30
	v_max_f32_e32 v26, 0, v25
	v_max_f32_e32 v25, v31, v31
	v_max_f32_e32 v27, v27, v27
	v_max_f32_e32 v28, 0, v28
	v_max_f32_e32 v29, 0, v29
	v_max_f32_e32 v24, 0, v24
	v_max_f32_e32 v25, 0, v25
	v_max_f32_e32 v27, 0, v27
	v_pk_mul_f32 v[28:29], v[28:29], v[28:29]
	v_pk_mul_f32 v[30:31], v[24:25], v[24:25]
	v_pk_mul_f32 v[34:35], v[26:27], v[26:27]
	v_max_f32_e32 v16, v16, v16
	v_max_f32_e32 v17, v17, v17
	v_cvt_pk_bf16_f32 v24, v28, v29
	v_cvt_pk_bf16_f32 v25, v30, v31
	v_cvt_pk_bf16_f32 v26, v32, v33
	v_cvt_pk_bf16_f32 v27, v34, v35
	v_max_f32_e32 v16, 0, v16
	v_max_f32_e32 v17, 0, v17
	global_store_dwordx4 v[88:89], v[24:27], off offset:64 sc1
	v_max_f32_e32 v20, v20, v20
	v_max_f32_e32 v21, v21, v21
	v_pk_mul_f32 v[24:25], v[16:17], v[16:17]
	v_max_f32_e32 v17, v18, v18
	v_max_f32_e32 v16, v22, v22
	v_max_f32_e32 v18, 0, v17
	v_max_f32_e32 v17, v23, v23
	v_max_f32_e32 v19, v19, v19
	v_max_f32_e32 v20, 0, v20
	v_max_f32_e32 v21, 0, v21
	v_max_f32_e32 v16, 0, v16
	v_max_f32_e32 v17, 0, v17
	v_max_f32_e32 v19, 0, v19
	v_pk_mul_f32 v[20:21], v[20:21], v[20:21]
	v_pk_mul_f32 v[22:23], v[16:17], v[16:17]
	v_pk_mul_f32 v[26:27], v[18:19], v[18:19]
	v_max_f32_e32 v8, v8, v8
	v_max_f32_e32 v9, v9, v9
	v_cvt_pk_bf16_f32 v16, v20, v21
	v_cvt_pk_bf16_f32 v17, v22, v23
	v_cvt_pk_bf16_f32 v18, v24, v25
	v_cvt_pk_bf16_f32 v19, v26, v27
	v_max_f32_e32 v8, 0, v8
	v_max_f32_e32 v9, 0, v9
	global_store_dwordx4 v[80:81], v[16:19], off offset:64 sc1
	v_max_f32_e32 v12, v12, v12
	v_max_f32_e32 v13, v13, v13
	v_pk_mul_f32 v[16:17], v[8:9], v[8:9]
	v_max_f32_e32 v9, v10, v10
	v_max_f32_e32 v8, v14, v14
	v_max_f32_e32 v10, 0, v9
	v_max_f32_e32 v9, v15, v15
	v_max_f32_e32 v11, v11, v11
	v_max_f32_e32 v12, 0, v12
	v_max_f32_e32 v13, 0, v13
	v_max_f32_e32 v8, 0, v8
	v_max_f32_e32 v9, 0, v9
	v_max_f32_e32 v11, 0, v11
	v_pk_mul_f32 v[12:13], v[12:13], v[12:13]
	v_pk_mul_f32 v[14:15], v[8:9], v[8:9]
	v_pk_mul_f32 v[18:19], v[10:11], v[10:11]
	v_max_f32_e32 v0, v0, v0
	v_max_f32_e32 v1, v1, v1
	v_cvt_pk_bf16_f32 v8, v12, v13
	v_cvt_pk_bf16_f32 v9, v14, v15
	v_cvt_pk_bf16_f32 v10, v16, v17
	v_cvt_pk_bf16_f32 v11, v18, v19
	v_max_f32_e32 v0, 0, v0
	v_max_f32_e32 v1, 0, v1
	global_store_dwordx4 v[64:65], v[8:11], off offset:64 sc1
	v_max_f32_e32 v4, v4, v4
	v_max_f32_e32 v5, v5, v5
	v_pk_mul_f32 v[8:9], v[0:1], v[0:1]
	v_max_f32_e32 v1, v2, v2
	v_max_f32_e32 v0, v6, v6
	v_max_f32_e32 v2, 0, v1
	v_max_f32_e32 v1, v7, v7
	v_max_f32_e32 v3, v3, v3
	v_max_f32_e32 v4, 0, v4
	v_max_f32_e32 v5, 0, v5
	v_max_f32_e32 v0, 0, v0
	v_max_f32_e32 v1, 0, v1
	v_max_f32_e32 v3, 0, v3
	v_pk_mul_f32 v[4:5], v[4:5], v[4:5]
	v_pk_mul_f32 v[6:7], v[0:1], v[0:1]
	v_pk_mul_f32 v[10:11], v[2:3], v[2:3]
	s_add_i32 s17, s17, s82
	s_add_i32 s4, s4, s33
	s_add_i32 s16, s16, s81
	v_cvt_pk_bf16_f32 v0, v4, v5
	v_cvt_pk_bf16_f32 v1, v6, v7
	v_cvt_pk_bf16_f32 v2, v8, v9
	v_cvt_pk_bf16_f32 v3, v10, v11
	s_cmpk_gt_i32 s17, 0x7ff
	global_store_dwordx4 v[48:49], v[0:3], off offset:64 sc1
	s_cbranch_scc1 .LBB0_227

; template <class F>
; __device__ __forceinline__ void gemm_big(const ALbf& al, const u16* __restrict__ Wt, int K, int m0, int n0, const F& f, u16* sm) {
;     ...
; #pragma unroll
;   for (int pq = 0; pq < 2; pq++)
; #pragma unroll
;     for (int j = 0; j < 8; j++)
;       f(m0 + wm * 128 + j * 16 + (lane & 15), n0 + wn * 64 + pq * 32 + (lane >> 4) * 8, acc[2 * pq][j], acc[2 * pq + 1][j]);
; }
; __device__ __forceinline__ uint4 pack8v(const f32x4& a, const f32x4& b) {
;   return make_uint4(pack2(a[0], a[1]), pack2(a[2], a[3]), pack2(b[0], b[1]), pack2(b[2], b[3]));
; }
; __global__ void __launch_bounds__(NTHR, 2) mega(P p, int ph_lo, int ph_hi) {
;     ...
;         auto f8 = [=] __device__(int m, int n, const f32x4& a, const f32x4& b) { *(uint4*)(p.B + (size_t)m * 1024 + n) = pack8v(a, b); };
;         gemm_big_jobs(ALbf{p.A, 1024}, ph == 6 ? p.Wout0 : p.Wout1, 1024, 8, f8, smu, bid, nb);
.LBB0_241:
	v_and_b32_e32 v128, 0xffffff80, v138
	v_add_u32_e32 v128, s61, v128
	v_and_b32_e32 v129, 64, v138
	v_and_or_b32 v128, v138, 15, v128
	v_lshlrev_b32_e32 v130, 3, v140
	v_or3_b32 v130, v130, v129, s60
	v_ashrrev_i32_e32 v129, 31, v128
	v_ashrrev_i32_e32 v131, 31, v130
	v_cvt_pk_bf16_f32 v124, v124, v125
	v_cvt_pk_bf16_f32 v125, v126, v127
	v_cvt_pk_bf16_f32 v126, v120, v121
	v_lshlrev_b64 v[120:121], 11, v[128:129]
	v_cvt_pk_bf16_f32 v127, v122, v123
	v_lshl_add_u64 v[120:121], s[20:21], 0, v[120:121]
	v_lshlrev_b64 v[122:123], 1, v[130:131]
	v_lshl_add_u64 v[120:121], v[120:121], 0, v[122:123]
	v_cvt_pk_bf16_f32 v52, v52, v53
	v_cvt_pk_bf16_f32 v53, v54, v55
	v_cvt_pk_bf16_f32 v55, v50, v51
	v_or_b32_e32 v50, 0x70, v128
	global_store_dwordx4 v[120:121], v[124:127], off sc1
	v_ashrrev_i32_e32 v51, 31, v50
	v_cvt_pk_bf16_f32 v116, v116, v117
	v_or_b32_e32 v124, 16, v128
	v_cvt_pk_bf16_f32 v117, v118, v119
	v_cvt_pk_bf16_f32 v119, v114, v115
	v_ashrrev_i32_e32 v125, 31, v124
	v_or_b32_e32 v114, 32, v128
	v_cvt_pk_bf16_f32 v36, v36, v37
	v_cvt_pk_bf16_f32 v37, v38, v39
	v_cvt_pk_bf16_f32 v38, v32, v33
	v_lshlrev_b64 v[32:33], 11, v[50:51]
	v_cvt_pk_bf16_f32 v118, v112, v113
	v_lshlrev_b64 v[112:113], 11, v[124:125]
	v_cvt_pk_bf16_f32 v108, v108, v109
	v_cvt_pk_bf16_f32 v109, v110, v111
	v_cvt_pk_bf16_f32 v111, v106, v107
	v_ashrrev_i32_e32 v115, 31, v114
	v_or_b32_e32 v106, 48, v128
	v_cvt_pk_bf16_f32 v100, v100, v101
	v_cvt_pk_bf16_f32 v101, v102, v103
	v_cvt_pk_bf16_f32 v103, v98, v99
	v_or_b32_e32 v98, 64, v128
	v_cvt_pk_bf16_f32 v92, v92, v93
	v_cvt_pk_bf16_f32 v93, v94, v95
	v_cvt_pk_bf16_f32 v95, v90, v91
	v_or_b32_e32 v90, 0x50, v128
	v_cvt_pk_bf16_f32 v72, v72, v73
	v_cvt_pk_bf16_f32 v73, v74, v75
	v_cvt_pk_bf16_f32 v75, v66, v67
	v_or_b32_e32 v66, 0x60, v128
	v_lshl_add_u64 v[32:33], s[20:21], 0, v[32:33]
	v_lshl_add_u64 v[112:113], s[20:21], 0, v[112:113]
	v_cvt_pk_bf16_f32 v110, v104, v105
	v_lshlrev_b64 v[104:105], 11, v[114:115]
	v_ashrrev_i32_e32 v107, 31, v106
	v_ashrrev_i32_e32 v99, 31, v98
	v_ashrrev_i32_e32 v91, 31, v90
	v_ashrrev_i32_e32 v67, 31, v66
	v_cvt_pk_bf16_f32 v39, v34, v35
	v_lshl_add_u64 v[50:51], v[32:33], 0, v[122:123]
	v_cvt_pk_bf16_f32 v32, v84, v85
	v_cvt_pk_bf16_f32 v33, v86, v87
	v_cvt_pk_bf16_f32 v34, v80, v81
	v_cvt_pk_bf16_f32 v35, v82, v83
	v_lshl_add_u64 v[112:113], v[112:113], 0, v[122:123]
	v_lshl_add_u64 v[104:105], s[20:21], 0, v[104:105]
	v_cvt_pk_bf16_f32 v102, v96, v97
	v_lshlrev_b64 v[96:97], 11, v[106:107]
	v_cvt_pk_bf16_f32 v94, v88, v89
	v_lshlrev_b64 v[88:89], 11, v[98:99]
	v_cvt_pk_bf16_f32 v74, v64, v65
	v_lshlrev_b64 v[64:65], 11, v[90:91]
	v_cvt_pk_bf16_f32 v54, v48, v49
	v_lshlrev_b64 v[48:49], 11, v[66:67]
	global_store_dwordx4 v[120:121], v[32:35], off offset:64 sc1
	v_lshl_add_u64 v[104:105], v[104:105], 0, v[122:123]
	v_lshl_add_u64 v[96:97], s[20:21], 0, v[96:97]
	v_cvt_pk_bf16_f32 v32, v76, v77
	v_cvt_pk_bf16_f32 v33, v78, v79
	v_cvt_pk_bf16_f32 v34, v68, v69
	v_cvt_pk_bf16_f32 v35, v70, v71
	v_lshl_add_u64 v[88:89], s[20:21], 0, v[88:89]
	v_lshl_add_u64 v[64:65], s[20:21], 0, v[64:65]
	v_lshl_add_u64 v[48:49], s[20:21], 0, v[48:49]
	global_store_dwordx4 v[112:113], v[32:35], off offset:64 sc1
	s_add_i32 s17, s17, s82
	s_add_i32 s4, s4, s33
	v_cvt_pk_bf16_f32 v32, v60, v61
	v_cvt_pk_bf16_f32 v33, v62, v63
	v_cvt_pk_bf16_f32 v34, v56, v57
	v_cvt_pk_bf16_f32 v35, v58, v59
	s_add_i32 s16, s16, s81
	v_lshl_add_u64 v[96:97], v[96:97], 0, v[122:123]
	v_lshl_add_u64 v[88:89], v[88:89], 0, v[122:123]
	v_lshl_add_u64 v[64:65], v[64:65], 0, v[122:123]
	v_lshl_add_u64 v[48:49], v[48:49], 0, v[122:123]
	global_store_dwordx4 v[104:105], v[32:35], off offset:64 sc1
	v_cvt_pk_bf16_f32 v28, v28, v29
	v_cvt_pk_bf16_f32 v29, v30, v31
	v_cvt_pk_bf16_f32 v32, v44, v45
	v_cvt_pk_bf16_f32 v33, v46, v47
	v_cvt_pk_bf16_f32 v34, v40, v41
	v_cvt_pk_bf16_f32 v35, v42, v43
	v_cvt_pk_bf16_f32 v30, v24, v25
	v_cvt_pk_bf16_f32 v31, v26, v27
	v_cvt_pk_bf16_f32 v20, v20, v21
	v_cvt_pk_bf16_f32 v21, v22, v23
	v_cvt_pk_bf16_f32 v22, v16, v17
	v_cvt_pk_bf16_f32 v23, v18, v19
	v_cvt_pk_bf16_f32 v12, v12, v13
	v_cvt_pk_bf16_f32 v13, v14, v15
	v_cvt_pk_bf16_f32 v14, v8, v9
	v_cvt_pk_bf16_f32 v15, v10, v11
	v_cvt_pk_bf16_f32 v4, v4, v5
	v_cvt_pk_bf16_f32 v5, v6, v7
	v_cvt_pk_bf16_f32 v6, v0, v1
	v_cvt_pk_bf16_f32 v7, v2, v3
	s_cmpk_gt_i32 s17, 0x1ff
	global_store_dwordx4 v[112:113], v[116:119], off sc1
	global_store_dwordx4 v[104:105], v[108:111], off sc1
	global_store_dwordx4 v[96:97], v[100:103], off sc1
	global_store_dwordx4 v[88:89], v[92:95], off sc1
	global_store_dwordx4 v[64:65], v[72:75], off sc1
	global_store_dwordx4 v[48:49], v[52:55], off sc1
	global_store_dwordx4 v[50:51], v[36:39], off sc1
	global_store_dwordx4 v[96:97], v[32:35], off offset:64 sc1
	global_store_dwordx4 v[88:89], v[28:31], off offset:64 sc1
	global_store_dwordx4 v[64:65], v[20:23], off offset:64 sc1
	global_store_dwordx4 v[48:49], v[12:15], off offset:64 sc1
	global_store_dwordx4 v[50:51], v[4:7], off offset:64 sc1
	s_cbranch_scc1 .LBB0_250

; template <class F>
; __device__ __forceinline__ void gemm_big(const ALbf& al, const u16* __restrict__ Wt, int K, int m0, int n0, const F& f, u16* sm) {
;     ...
; #pragma unroll
;   for (int pq = 0; pq < 2; pq++)
; #pragma unroll
;     for (int j = 0; j < 8; j++)
;       f(m0 + wm * 128 + j * 16 + (lane & 15), n0 + wn * 64 + pq * 32 + (lane >> 4) * 8, acc[2 * pq][j], acc[2 * pq + 1][j]);
; }
; __device__ __forceinline__ uint4 pack8v(const f32x4& a, const f32x4& b) {
;   return make_uint4(pack2(a[0], a[1]), pack2(a[2], a[3]), pack2(b[0], b[1]), pack2(b[2], b[3]));
; }
; __global__ void __launch_bounds__(NTHR, 2) mega(P p, int ph_lo, int ph_hi) {
;     ...
;         auto f8 = [=] __device__(int m, int n, const f32x4& a, const f32x4& b) { *(uint4*)(p.B + (size_t)m * 1024 + n) = pack8v(a, b); };
;         gemm_big_jobs(ALbf{p.A, 1024}, p.Wq, 1024, 8, f8, smu, bid, nb);
.LBB0_256:
	v_and_b32_e32 v128, 0xffffff80, v138
	v_add_u32_e32 v128, s17, v128
	v_and_b32_e32 v129, 64, v138
	v_and_or_b32 v128, v138, 15, v128
	v_lshlrev_b32_e32 v130, 3, v140
	v_or3_b32 v130, v130, v129, s16
	v_ashrrev_i32_e32 v129, 31, v128
	v_ashrrev_i32_e32 v131, 31, v130
	v_cvt_pk_bf16_f32 v124, v124, v125
	v_cvt_pk_bf16_f32 v125, v126, v127
	v_cvt_pk_bf16_f32 v126, v120, v121
	v_lshlrev_b64 v[120:121], 11, v[128:129]
	v_cvt_pk_bf16_f32 v127, v122, v123
	v_lshl_add_u64 v[120:121], s[20:21], 0, v[120:121]
	v_lshlrev_b64 v[122:123], 1, v[130:131]
	v_lshl_add_u64 v[120:121], v[120:121], 0, v[122:123]
	v_cvt_pk_bf16_f32 v52, v52, v53
	v_cvt_pk_bf16_f32 v53, v54, v55
	v_cvt_pk_bf16_f32 v55, v50, v51
	v_or_b32_e32 v50, 0x70, v128
	global_store_dwordx4 v[120:121], v[124:127], off sc1
	v_ashrrev_i32_e32 v51, 31, v50
	v_cvt_pk_bf16_f32 v116, v116, v117
	v_or_b32_e32 v124, 16, v128
	v_cvt_pk_bf16_f32 v117, v118, v119
	v_cvt_pk_bf16_f32 v119, v114, v115
	v_ashrrev_i32_e32 v125, 31, v124
	v_or_b32_e32 v114, 32, v128
	v_cvt_pk_bf16_f32 v36, v36, v37
	v_cvt_pk_bf16_f32 v37, v38, v39
	v_cvt_pk_bf16_f32 v38, v32, v33
	v_lshlrev_b64 v[32:33], 11, v[50:51]
	v_cvt_pk_bf16_f32 v118, v112, v113
	v_lshlrev_b64 v[112:113], 11, v[124:125]
	v_cvt_pk_bf16_f32 v108, v108, v109
	v_cvt_pk_bf16_f32 v109, v110, v111
	v_cvt_pk_bf16_f32 v111, v106, v107
	v_ashrrev_i32_e32 v115, 31, v114
	v_or_b32_e32 v106, 48, v128
	v_cvt_pk_bf16_f32 v100, v100, v101
	v_cvt_pk_bf16_f32 v101, v102, v103
	v_cvt_pk_bf16_f32 v103, v98, v99
	v_or_b32_e32 v98, 64, v128
	v_cvt_pk_bf16_f32 v92, v92, v93
	v_cvt_pk_bf16_f32 v93, v94, v95
	v_cvt_pk_bf16_f32 v95, v90, v91
	v_or_b32_e32 v90, 0x50, v128
	v_cvt_pk_bf16_f32 v72, v72, v73
	v_cvt_pk_bf16_f32 v73, v74, v75
	v_cvt_pk_bf16_f32 v75, v66, v67
	v_or_b32_e32 v66, 0x60, v128
	v_lshl_add_u64 v[32:33], s[20:21], 0, v[32:33]
	v_lshl_add_u64 v[112:113], s[20:21], 0, v[112:113]
	v_cvt_pk_bf16_f32 v110, v104, v105
	v_lshlrev_b64 v[104:105], 11, v[114:115]
	v_ashrrev_i32_e32 v107, 31, v106
	v_ashrrev_i32_e32 v99, 31, v98
	v_ashrrev_i32_e32 v91, 31, v90
	v_ashrrev_i32_e32 v67, 31, v66
	v_cvt_pk_bf16_f32 v39, v34, v35
	v_lshl_add_u64 v[50:51], v[32:33], 0, v[122:123]
	v_cvt_pk_bf16_f32 v32, v84, v85
	v_cvt_pk_bf16_f32 v33, v86, v87
	v_cvt_pk_bf16_f32 v34, v80, v81
	v_cvt_pk_bf16_f32 v35, v82, v83
	v_lshl_add_u64 v[112:113], v[112:113], 0, v[122:123]
	v_lshl_add_u64 v[104:105], s[20:21], 0, v[104:105]
	v_cvt_pk_bf16_f32 v102, v96, v97
	v_lshlrev_b64 v[96:97], 11, v[106:107]
	v_cvt_pk_bf16_f32 v94, v88, v89
	v_lshlrev_b64 v[88:89], 11, v[98:99]
	v_cvt_pk_bf16_f32 v74, v64, v65
	v_lshlrev_b64 v[64:65], 11, v[90:91]
	v_cvt_pk_bf16_f32 v54, v48, v49
	v_lshlrev_b64 v[48:49], 11, v[66:67]
	global_store_dwordx4 v[120:121], v[32:35], off offset:64 sc1
	v_lshl_add_u64 v[104:105], v[104:105], 0, v[122:123]
	v_lshl_add_u64 v[96:97], s[20:21], 0, v[96:97]
	v_cvt_pk_bf16_f32 v32, v76, v77
	v_cvt_pk_bf16_f32 v33, v78, v79
	v_cvt_pk_bf16_f32 v34, v68, v69
	v_cvt_pk_bf16_f32 v35, v70, v71
	v_lshl_add_u64 v[88:89], s[20:21], 0, v[88:89]
	v_lshl_add_u64 v[64:65], s[20:21], 0, v[64:65]
	v_lshl_add_u64 v[48:49], s[20:21], 0, v[48:49]
	global_store_dwordx4 v[112:113], v[32:35], off offset:64 sc1
	s_add_i32 s15, s15, s82
	s_add_i32 s4, s4, s33
	v_cvt_pk_bf16_f32 v32, v60, v61
	v_cvt_pk_bf16_f32 v33, v62, v63
	v_cvt_pk_bf16_f32 v34, v56, v57
	v_cvt_pk_bf16_f32 v35, v58, v59
	s_add_i32 s14, s14, s81
	v_lshl_add_u64 v[96:97], v[96:97], 0, v[122:123]
	v_lshl_add_u64 v[88:89], v[88:89], 0, v[122:123]
	v_lshl_add_u64 v[64:65], v[64:65], 0, v[122:123]
	v_lshl_add_u64 v[48:49], v[48:49], 0, v[122:123]
	global_store_dwordx4 v[104:105], v[32:35], off offset:64 sc1
	v_cvt_pk_bf16_f32 v28, v28, v29
	v_cvt_pk_bf16_f32 v29, v30, v31
	v_cvt_pk_bf16_f32 v32, v44, v45
	v_cvt_pk_bf16_f32 v33, v46, v47
	v_cvt_pk_bf16_f32 v34, v40, v41
	v_cvt_pk_bf16_f32 v35, v42, v43
	v_cvt_pk_bf16_f32 v30, v24, v25
	v_cvt_pk_bf16_f32 v31, v26, v27
	v_cvt_pk_bf16_f32 v20, v20, v21
	v_cvt_pk_bf16_f32 v21, v22, v23
	v_cvt_pk_bf16_f32 v22, v16, v17
	v_cvt_pk_bf16_f32 v23, v18, v19
	v_cvt_pk_bf16_f32 v12, v12, v13
	v_cvt_pk_bf16_f32 v13, v14, v15
	v_cvt_pk_bf16_f32 v14, v8, v9
	v_cvt_pk_bf16_f32 v15, v10, v11
	v_cvt_pk_bf16_f32 v4, v4, v5
	v_cvt_pk_bf16_f32 v5, v6, v7
	v_cvt_pk_bf16_f32 v6, v0, v1
	v_cvt_pk_bf16_f32 v7, v2, v3
	s_cmpk_gt_i32 s15, 0x1ff
	global_store_dwordx4 v[112:113], v[116:119], off sc1
	global_store_dwordx4 v[104:105], v[108:111], off sc1
	global_store_dwordx4 v[96:97], v[100:103], off sc1
	global_store_dwordx4 v[88:89], v[92:95], off sc1
	global_store_dwordx4 v[64:65], v[72:75], off sc1
	global_store_dwordx4 v[48:49], v[52:55], off sc1
	global_store_dwordx4 v[50:51], v[36:39], off sc1
	global_store_dwordx4 v[96:97], v[32:35], off offset:64 sc1
	global_store_dwordx4 v[88:89], v[28:31], off offset:64 sc1
	global_store_dwordx4 v[64:65], v[20:23], off offset:64 sc1
	global_store_dwordx4 v[48:49], v[12:15], off offset:64 sc1
	global_store_dwordx4 v[50:51], v[4:7], off offset:64 sc1
	s_cbranch_scc1 .LBB0_265

; template <class F>
; __device__ __forceinline__ void gemm_big(const ALbf& al, const u16* __restrict__ Wt, int K, int m0, int n0, const F& f, u16* sm) {
;     ...
; #pragma unroll
;   for (int pq = 0; pq < 2; pq++)
; #pragma unroll
;     for (int j = 0; j < 8; j++)
;       f(m0 + wm * 128 + j * 16 + (lane & 15), n0 + wn * 64 + pq * 32 + (lane >> 4) * 8, acc[2 * pq][j], acc[2 * pq + 1][j]);
; }
; __device__ __forceinline__ uint4 pack8v(const f32x4& a, const f32x4& b) {
;   return make_uint4(pack2(a[0], a[1]), pack2(a[2], a[3]), pack2(b[0], b[1]), pack2(b[2], b[3]));
; }
; __global__ void __launch_bounds__(NTHR, 2) mega(P p, int ph_lo, int ph_hi) {
;     ...
;         auto f8 = [=] __device__(int m, int n, const f32x4& a, const f32x4& b) { *(uint4*)(p.B + (size_t)m * 1024 + n) = pack8v(a, b); };
;         gemm_big_jobs(ALbf{p.A, 1024}, p.Wo, 1024, 8, f8, smu, bid, nb);
.LBB0_278:
	v_and_b32_e32 v128, 0xffffff80, v138
	v_add_u32_e32 v128, s15, v128
	v_and_b32_e32 v129, 64, v138
	v_and_or_b32 v128, v138, 15, v128
	v_lshlrev_b32_e32 v130, 3, v140
	v_or3_b32 v130, v130, v129, s14
	v_ashrrev_i32_e32 v129, 31, v128
	v_ashrrev_i32_e32 v131, 31, v130
	v_cvt_pk_bf16_f32 v124, v124, v125
	v_cvt_pk_bf16_f32 v125, v126, v127
	v_cvt_pk_bf16_f32 v126, v120, v121
	v_lshlrev_b64 v[120:121], 11, v[128:129]
	v_cvt_pk_bf16_f32 v127, v122, v123
	v_lshl_add_u64 v[120:121], s[20:21], 0, v[120:121]
	v_lshlrev_b64 v[122:123], 1, v[130:131]
	v_lshl_add_u64 v[120:121], v[120:121], 0, v[122:123]
	v_cvt_pk_bf16_f32 v52, v52, v53
	v_cvt_pk_bf16_f32 v53, v54, v55
	v_cvt_pk_bf16_f32 v55, v50, v51
	v_or_b32_e32 v50, 0x70, v128
	global_store_dwordx4 v[120:121], v[124:127], off sc1
	v_ashrrev_i32_e32 v51, 31, v50
	v_cvt_pk_bf16_f32 v116, v116, v117
	v_or_b32_e32 v124, 16, v128
	v_cvt_pk_bf16_f32 v117, v118, v119
	v_cvt_pk_bf16_f32 v119, v114, v115
	v_ashrrev_i32_e32 v125, 31, v124
	v_or_b32_e32 v114, 32, v128
	v_cvt_pk_bf16_f32 v36, v36, v37
	v_cvt_pk_bf16_f32 v37, v38, v39
	v_cvt_pk_bf16_f32 v38, v32, v33
	v_lshlrev_b64 v[32:33], 11, v[50:51]
	v_cvt_pk_bf16_f32 v118, v112, v113
	v_lshlrev_b64 v[112:113], 11, v[124:125]
	v_cvt_pk_bf16_f32 v108, v108, v109
	v_cvt_pk_bf16_f32 v109, v110, v111
	v_cvt_pk_bf16_f32 v111, v106, v107
	v_ashrrev_i32_e32 v115, 31, v114
	v_or_b32_e32 v106, 48, v128
	v_cvt_pk_bf16_f32 v100, v100, v101
	v_cvt_pk_bf16_f32 v101, v102, v103
	v_cvt_pk_bf16_f32 v103, v98, v99
	v_or_b32_e32 v98, 64, v128
	v_cvt_pk_bf16_f32 v92, v92, v93
	v_cvt_pk_bf16_f32 v93, v94, v95
	v_cvt_pk_bf16_f32 v95, v90, v91
	v_or_b32_e32 v90, 0x50, v128
	v_cvt_pk_bf16_f32 v72, v72, v73
	v_cvt_pk_bf16_f32 v73, v74, v75
	v_cvt_pk_bf16_f32 v75, v66, v67
	v_or_b32_e32 v66, 0x60, v128
	v_lshl_add_u64 v[32:33], s[20:21], 0, v[32:33]
	v_lshl_add_u64 v[112:113], s[20:21], 0, v[112:113]
	v_cvt_pk_bf16_f32 v110, v104, v105
	v_lshlrev_b64 v[104:105], 11, v[114:115]
	v_ashrrev_i32_e32 v107, 31, v106
	v_ashrrev_i32_e32 v99, 31, v98
	v_ashrrev_i32_e32 v91, 31, v90
	v_ashrrev_i32_e32 v67, 31, v66
	v_cvt_pk_bf16_f32 v39, v34, v35
	v_lshl_add_u64 v[50:51], v[32:33], 0, v[122:123]
	v_cvt_pk_bf16_f32 v32, v84, v85
	v_cvt_pk_bf16_f32 v33, v86, v87
	v_cvt_pk_bf16_f32 v34, v80, v81
	v_cvt_pk_bf16_f32 v35, v82, v83
	v_lshl_add_u64 v[112:113], v[112:113], 0, v[122:123]
	v_lshl_add_u64 v[104:105], s[20:21], 0, v[104:105]
	v_cvt_pk_bf16_f32 v102, v96, v97
	v_lshlrev_b64 v[96:97], 11, v[106:107]
	v_cvt_pk_bf16_f32 v94, v88, v89
	v_lshlrev_b64 v[88:89], 11, v[98:99]
	v_cvt_pk_bf16_f32 v74, v64, v65
	v_lshlrev_b64 v[64:65], 11, v[90:91]
	v_cvt_pk_bf16_f32 v54, v48, v49
	v_lshlrev_b64 v[48:49], 11, v[66:67]
	global_store_dwordx4 v[120:121], v[32:35], off offset:64 sc1
	v_lshl_add_u64 v[104:105], v[104:105], 0, v[122:123]
	v_lshl_add_u64 v[96:97], s[20:21], 0, v[96:97]
	v_cvt_pk_bf16_f32 v32, v76, v77
	v_cvt_pk_bf16_f32 v33, v78, v79
	v_cvt_pk_bf16_f32 v34, v68, v69
	v_cvt_pk_bf16_f32 v35, v70, v71
	v_lshl_add_u64 v[88:89], s[20:21], 0, v[88:89]
	v_lshl_add_u64 v[64:65], s[20:21], 0, v[64:65]
	v_lshl_add_u64 v[48:49], s[20:21], 0, v[48:49]
	global_store_dwordx4 v[112:113], v[32:35], off offset:64 sc1
	s_add_i32 s13, s13, s82
	s_add_i32 s4, s4, s33
	v_cvt_pk_bf16_f32 v32, v60, v61
	v_cvt_pk_bf16_f32 v33, v62, v63
	v_cvt_pk_bf16_f32 v34, v56, v57
	v_cvt_pk_bf16_f32 v35, v58, v59
	s_add_i32 s12, s12, s81
	v_lshl_add_u64 v[96:97], v[96:97], 0, v[122:123]
	v_lshl_add_u64 v[88:89], v[88:89], 0, v[122:123]
	v_lshl_add_u64 v[64:65], v[64:65], 0, v[122:123]
	v_lshl_add_u64 v[48:49], v[48:49], 0, v[122:123]
	global_store_dwordx4 v[104:105], v[32:35], off offset:64 sc1
	v_cvt_pk_bf16_f32 v28, v28, v29
	v_cvt_pk_bf16_f32 v29, v30, v31
	v_cvt_pk_bf16_f32 v32, v44, v45
	v_cvt_pk_bf16_f32 v33, v46, v47
	v_cvt_pk_bf16_f32 v34, v40, v41
	v_cvt_pk_bf16_f32 v35, v42, v43
	v_cvt_pk_bf16_f32 v30, v24, v25
	v_cvt_pk_bf16_f32 v31, v26, v27
	v_cvt_pk_bf16_f32 v20, v20, v21
	v_cvt_pk_bf16_f32 v21, v22, v23
	v_cvt_pk_bf16_f32 v22, v16, v17
	v_cvt_pk_bf16_f32 v23, v18, v19
	v_cvt_pk_bf16_f32 v12, v12, v13
	v_cvt_pk_bf16_f32 v13, v14, v15
	v_cvt_pk_bf16_f32 v14, v8, v9
	v_cvt_pk_bf16_f32 v15, v10, v11
	v_cvt_pk_bf16_f32 v4, v4, v5
	v_cvt_pk_bf16_f32 v5, v6, v7
	v_cvt_pk_bf16_f32 v6, v0, v1
	v_cvt_pk_bf16_f32 v7, v2, v3
	s_cmpk_gt_i32 s13, 0x1ff
	global_store_dwordx4 v[112:113], v[116:119], off sc1
	global_store_dwordx4 v[104:105], v[108:111], off sc1
	global_store_dwordx4 v[96:97], v[100:103], off sc1
	global_store_dwordx4 v[88:89], v[92:95], off sc1
	global_store_dwordx4 v[64:65], v[72:75], off sc1
	global_store_dwordx4 v[48:49], v[52:55], off sc1
	global_store_dwordx4 v[50:51], v[36:39], off sc1
	global_store_dwordx4 v[96:97], v[32:35], off offset:64 sc1
	global_store_dwordx4 v[88:89], v[28:31], off offset:64 sc1
	global_store_dwordx4 v[64:65], v[20:23], off offset:64 sc1
	global_store_dwordx4 v[48:49], v[12:15], off offset:64 sc1
	global_store_dwordx4 v[50:51], v[4:7], off offset:64 sc1
	s_cbranch_scc1 .LBB0_287

; template <class F>
; __device__ __forceinline__ void gemm_big(const ALbf& al, const u16* __restrict__ Wt, int K, int m0, int n0, const F& f, u16* sm) {
;     ...
; #pragma unroll
;   for (int pq = 0; pq < 2; pq++)
; #pragma unroll
;     for (int j = 0; j < 8; j++)
;       f(m0 + wm * 128 + j * 16 + (lane & 15), n0 + wn * 64 + pq * 32 + (lane >> 4) * 8, acc[2 * pq][j], acc[2 * pq + 1][j]);
; }
; __device__ __forceinline__ uint4 pack8v(const f32x4& a, const f32x4& b) {
;   return make_uint4(pack2(a[0], a[1]), pack2(a[2], a[3]), pack2(b[0], b[1]), pack2(b[2], b[3]));
; }
; __global__ void __launch_bounds__(NTHR, 2) mega(P p, int ph_lo, int ph_hi) {
;     ...
;         auto f8 = [=] __device__(int m, int n, const f32x4& a, const f32x4& b) { *(uint4*)(p.B + (size_t)m * 1024 + n) = pack8v(a, b); };
;         gemm_big_jobs(ALbf{(const u16*)p.H, 4096}, p.W2, 4096, 8, f8, smu, bid, nb);
.LBB0_321:
	v_and_b32_e32 v128, 0xffffff80, v138
	v_add_u32_e32 v128, s61, v128
	v_and_b32_e32 v129, 64, v138
	v_and_or_b32 v128, v138, 15, v128
	v_lshlrev_b32_e32 v130, 3, v140
	v_or3_b32 v130, v130, v129, s60
	v_ashrrev_i32_e32 v129, 31, v128
	v_ashrrev_i32_e32 v131, 31, v130
	v_cvt_pk_bf16_f32 v124, v124, v125
	v_cvt_pk_bf16_f32 v125, v126, v127
	v_cvt_pk_bf16_f32 v126, v120, v121
	v_lshlrev_b64 v[120:121], 11, v[128:129]
	v_cvt_pk_bf16_f32 v127, v122, v123
	v_lshl_add_u64 v[120:121], s[20:21], 0, v[120:121]
	v_lshlrev_b64 v[122:123], 1, v[130:131]
	v_lshl_add_u64 v[120:121], v[120:121], 0, v[122:123]
	v_cvt_pk_bf16_f32 v52, v52, v53
	v_cvt_pk_bf16_f32 v53, v54, v55
	v_cvt_pk_bf16_f32 v55, v50, v51
	v_or_b32_e32 v50, 0x70, v128
	global_store_dwordx4 v[120:121], v[124:127], off sc1
	v_ashrrev_i32_e32 v51, 31, v50
	v_cvt_pk_bf16_f32 v116, v116, v117
	v_or_b32_e32 v124, 16, v128
	v_cvt_pk_bf16_f32 v117, v118, v119
	v_cvt_pk_bf16_f32 v119, v114, v115
	v_ashrrev_i32_e32 v125, 31, v124
	v_or_b32_e32 v114, 32, v128
	v_cvt_pk_bf16_f32 v36, v36, v37
	v_cvt_pk_bf16_f32 v37, v38, v39
	v_cvt_pk_bf16_f32 v38, v32, v33
	v_lshlrev_b64 v[32:33], 11, v[50:51]
	v_cvt_pk_bf16_f32 v118, v112, v113
	v_lshlrev_b64 v[112:113], 11, v[124:125]
	v_cvt_pk_bf16_f32 v108, v108, v109
	v_cvt_pk_bf16_f32 v109, v110, v111
	v_cvt_pk_bf16_f32 v111, v106, v107
	v_ashrrev_i32_e32 v115, 31, v114
	v_or_b32_e32 v106, 48, v128
	v_cvt_pk_bf16_f32 v100, v100, v101
	v_cvt_pk_bf16_f32 v101, v102, v103
	v_cvt_pk_bf16_f32 v103, v98, v99
	v_or_b32_e32 v98, 64, v128
	v_cvt_pk_bf16_f32 v92, v92, v93
	v_cvt_pk_bf16_f32 v93, v94, v95
	v_cvt_pk_bf16_f32 v95, v90, v91
	v_or_b32_e32 v90, 0x50, v128
	v_cvt_pk_bf16_f32 v72, v72, v73
	v_cvt_pk_bf16_f32 v73, v74, v75
	v_cvt_pk_bf16_f32 v75, v66, v67
	v_or_b32_e32 v66, 0x60, v128
	v_lshl_add_u64 v[32:33], s[20:21], 0, v[32:33]
	v_lshl_add_u64 v[112:113], s[20:21], 0, v[112:113]
	v_cvt_pk_bf16_f32 v110, v104, v105
	v_lshlrev_b64 v[104:105], 11, v[114:115]
	v_ashrrev_i32_e32 v107, 31, v106
	v_ashrrev_i32_e32 v99, 31, v98
	v_ashrrev_i32_e32 v91, 31, v90
	v_ashrrev_i32_e32 v67, 31, v66
	v_cvt_pk_bf16_f32 v39, v34, v35
	v_lshl_add_u64 v[50:51], v[32:33], 0, v[122:123]
	v_cvt_pk_bf16_f32 v32, v84, v85
	v_cvt_pk_bf16_f32 v33, v86, v87
	v_cvt_pk_bf16_f32 v34, v80, v81
	v_cvt_pk_bf16_f32 v35, v82, v83
	v_lshl_add_u64 v[112:113], v[112:113], 0, v[122:123]
	v_lshl_add_u64 v[104:105], s[20:21], 0, v[104:105]
	v_cvt_pk_bf16_f32 v102, v96, v97
	v_lshlrev_b64 v[96:97], 11, v[106:107]
	v_cvt_pk_bf16_f32 v94, v88, v89
	v_lshlrev_b64 v[88:89], 11, v[98:99]
	v_cvt_pk_bf16_f32 v74, v64, v65
	v_lshlrev_b64 v[64:65], 11, v[90:91]
	v_cvt_pk_bf16_f32 v54, v48, v49
	v_lshlrev_b64 v[48:49], 11, v[66:67]
	global_store_dwordx4 v[120:121], v[32:35], off offset:64 sc1
	v_lshl_add_u64 v[104:105], v[104:105], 0, v[122:123]
	v_lshl_add_u64 v[96:97], s[20:21], 0, v[96:97]
	v_cvt_pk_bf16_f32 v32, v76, v77
	v_cvt_pk_bf16_f32 v33, v78, v79
	v_cvt_pk_bf16_f32 v34, v68, v69
	v_cvt_pk_bf16_f32 v35, v70, v71
	v_lshl_add_u64 v[88:89], s[20:21], 0, v[88:89]
	v_lshl_add_u64 v[64:65], s[20:21], 0, v[64:65]
	v_lshl_add_u64 v[48:49], s[20:21], 0, v[48:49]
	global_store_dwordx4 v[112:113], v[32:35], off offset:64 sc1
	s_add_i32 s59, s59, s82
	s_add_i32 s4, s4, s33
	v_cvt_pk_bf16_f32 v32, v60, v61
	v_cvt_pk_bf16_f32 v33, v62, v63
	v_cvt_pk_bf16_f32 v34, v56, v57
	v_cvt_pk_bf16_f32 v35, v58, v59
	s_add_i32 s35, s35, s81
	v_lshl_add_u64 v[96:97], v[96:97], 0, v[122:123]
	v_lshl_add_u64 v[88:89], v[88:89], 0, v[122:123]
	v_lshl_add_u64 v[64:65], v[64:65], 0, v[122:123]
	v_lshl_add_u64 v[48:49], v[48:49], 0, v[122:123]
	global_store_dwordx4 v[104:105], v[32:35], off offset:64 sc1
	v_cvt_pk_bf16_f32 v28, v28, v29
	v_cvt_pk_bf16_f32 v29, v30, v31
	v_cvt_pk_bf16_f32 v32, v44, v45
	v_cvt_pk_bf16_f32 v33, v46, v47
	v_cvt_pk_bf16_f32 v34, v40, v41
	v_cvt_pk_bf16_f32 v35, v42, v43
	v_cvt_pk_bf16_f32 v30, v24, v25
	v_cvt_pk_bf16_f32 v31, v26, v27
	v_cvt_pk_bf16_f32 v20, v20, v21
	v_cvt_pk_bf16_f32 v21, v22, v23
	v_cvt_pk_bf16_f32 v22, v16, v17
	v_cvt_pk_bf16_f32 v23, v18, v19
	v_cvt_pk_bf16_f32 v12, v12, v13
	v_cvt_pk_bf16_f32 v13, v14, v15
	v_cvt_pk_bf16_f32 v14, v8, v9
	v_cvt_pk_bf16_f32 v15, v10, v11
	v_cvt_pk_bf16_f32 v4, v4, v5
	v_cvt_pk_bf16_f32 v5, v6, v7
	v_cvt_pk_bf16_f32 v6, v0, v1
	v_cvt_pk_bf16_f32 v7, v2, v3
	s_cmpk_gt_i32 s59, 0x1ff
	global_store_dwordx4 v[112:113], v[116:119], off sc1
	global_store_dwordx4 v[104:105], v[108:111], off sc1
	global_store_dwordx4 v[96:97], v[100:103], off sc1
	global_store_dwordx4 v[88:89], v[92:95], off sc1
	global_store_dwordx4 v[64:65], v[72:75], off sc1
	global_store_dwordx4 v[48:49], v[52:55], off sc1
	global_store_dwordx4 v[50:51], v[36:39], off sc1
	global_store_dwordx4 v[96:97], v[32:35], off offset:64 sc1
	global_store_dwordx4 v[88:89], v[28:31], off offset:64 sc1
	global_store_dwordx4 v[64:65], v[20:23], off offset:64 sc1
	global_store_dwordx4 v[48:49], v[12:15], off offset:64 sc1
	global_store_dwordx4 v[50:51], v[4:7], off offset:64 sc1
	s_cbranch_scc1 .LBB0_330

; template <class F>
; __device__ __forceinline__ void gemm_big(const ALbf& al, const u16* __restrict__ Wt, int K, int m0, int n0, const F& f, u16* sm) {
;     ...
; #pragma unroll
;   for (int pq = 0; pq < 2; pq++)
; #pragma unroll
;     for (int j = 0; j < 8; j++)
;       f(m0 + wm * 128 + j * 16 + (lane & 15), n0 + wn * 64 + pq * 32 + (lane >> 4) * 8, acc[2 * pq][j], acc[2 * pq + 1][j]);
; }
; __device__ __forceinline__ uint4 pack8v(const f32x4& a, const f32x4& b) {
;   return make_uint4(pack2(a[0], a[1]), pack2(a[2], a[3]), pack2(b[0], b[1]), pack2(b[2], b[3]));
; }
; __global__ void __launch_bounds__(NTHR, 2) mega(P p, int ph_lo, int ph_hi) {
;     ...
;         auto f8 = [=] __device__(int m, int n, const f32x4& a, const f32x4& b) {
;           *(uint4*)((u16*)p.H + (size_t)m * PROJ0_LD + n) = pack8v(a, b);
;         };
;         gemm_big_jobs(ALbf{p.A, 1024}, p.Win0, 1024, 16, f8, smu, bid, nb);
.LBB0_520:
	v_and_b32_e32 v129, 0xffffff80, v138
	v_add_u32_e32 v129, s15, v129
	v_and_b32_e32 v128, 64, v138
	v_and_or_b32 v130, v138, 15, v129
	v_lshlrev_b32_e32 v129, 3, v140
	v_or3_b32 v128, v129, v128, s14
	v_ashrrev_i32_e32 v129, 31, v128
	v_cvt_pk_bf16_f32 v124, v124, v125
	v_cvt_pk_bf16_f32 v125, v126, v127
	v_cvt_pk_bf16_f32 v126, v120, v121
	v_mov_b64_e32 v[120:121], s[22:23]
	v_cvt_pk_bf16_f32 v127, v122, v123
	v_mad_i64_i32 v[122:123], s[6:7], v130, s52, v[120:121]
	v_lshlrev_b64 v[128:129], 1, v[128:129]
	v_lshl_add_u64 v[122:123], v[122:123], 0, v[128:129]
	v_cvt_pk_bf16_f32 v52, v52, v53
	v_cvt_pk_bf16_f32 v53, v54, v55
	v_cvt_pk_bf16_f32 v55, v50, v51
	v_or_b32_e32 v50, 0x70, v130
	global_store_dwordx4 v[122:123], v[124:127], off sc1
	v_cvt_pk_bf16_f32 v36, v36, v37
	v_cvt_pk_bf16_f32 v37, v38, v39
	v_or_b32_e32 v124, 16, v130
	v_cvt_pk_bf16_f32 v38, v32, v33
	v_mad_i64_i32 v[32:33], s[6:7], v50, s52, v[120:121]
	v_cvt_pk_bf16_f32 v116, v116, v117
	v_cvt_pk_bf16_f32 v117, v118, v119
	v_cvt_pk_bf16_f32 v118, v112, v113
	v_cvt_pk_bf16_f32 v119, v114, v115
	v_mad_i64_i32 v[112:113], s[6:7], v124, s52, v[120:121]
	v_or_b32_e32 v114, 32, v130
	v_cvt_pk_bf16_f32 v39, v34, v35
	v_lshl_add_u64 v[50:51], v[32:33], 0, v[128:129]
	v_cvt_pk_bf16_f32 v32, v92, v93
	v_cvt_pk_bf16_f32 v33, v94, v95
	v_cvt_pk_bf16_f32 v34, v88, v89
	v_cvt_pk_bf16_f32 v35, v90, v91
	v_lshl_add_u64 v[112:113], v[112:113], 0, v[128:129]
	v_cvt_pk_bf16_f32 v108, v108, v109
	v_cvt_pk_bf16_f32 v109, v110, v111
	v_cvt_pk_bf16_f32 v110, v104, v105
	v_cvt_pk_bf16_f32 v111, v106, v107
	v_mad_i64_i32 v[104:105], s[6:7], v114, s52, v[120:121]
	v_or_b32_e32 v106, 48, v130
	v_cvt_pk_bf16_f32 v100, v100, v101
	v_cvt_pk_bf16_f32 v101, v102, v103
	v_cvt_pk_bf16_f32 v103, v98, v99
	v_or_b32_e32 v98, 64, v130
	v_cvt_pk_bf16_f32 v84, v84, v85
	v_cvt_pk_bf16_f32 v85, v86, v87
	v_cvt_pk_bf16_f32 v87, v82, v83
	v_or_b32_e32 v82, 0x50, v130
	v_cvt_pk_bf16_f32 v68, v68, v69
	v_cvt_pk_bf16_f32 v69, v70, v71
	v_cvt_pk_bf16_f32 v71, v66, v67
	v_or_b32_e32 v66, 0x60, v130
	global_store_dwordx4 v[122:123], v[32:35], off offset:64 sc1
	v_lshl_add_u64 v[104:105], v[104:105], 0, v[128:129]
	v_cvt_pk_bf16_f32 v102, v96, v97
	v_cvt_pk_bf16_f32 v32, v76, v77
	v_cvt_pk_bf16_f32 v33, v78, v79
	v_cvt_pk_bf16_f32 v34, v72, v73
	v_cvt_pk_bf16_f32 v35, v74, v75
	v_mad_i64_i32 v[96:97], s[6:7], v106, s52, v[120:121]
	v_cvt_pk_bf16_f32 v86, v80, v81
	v_mad_i64_i32 v[80:81], s[6:7], v98, s52, v[120:121]
	v_cvt_pk_bf16_f32 v70, v64, v65
	v_mad_i64_i32 v[64:65], s[6:7], v82, s52, v[120:121]
	v_cvt_pk_bf16_f32 v54, v48, v49
	v_mad_i64_i32 v[48:49], s[6:7], v66, s52, v[120:121]
	global_store_dwordx4 v[112:113], v[32:35], off offset:64 sc1
	s_add_i32 s13, s13, s82
	s_add_i32 s4, s4, s33
	v_cvt_pk_bf16_f32 v32, v60, v61
	v_cvt_pk_bf16_f32 v33, v62, v63
	v_cvt_pk_bf16_f32 v34, v56, v57
	v_cvt_pk_bf16_f32 v35, v58, v59
	s_add_i32 s12, s12, s81
	v_lshl_add_u64 v[96:97], v[96:97], 0, v[128:129]
	v_lshl_add_u64 v[80:81], v[80:81], 0, v[128:129]
	v_lshl_add_u64 v[64:65], v[64:65], 0, v[128:129]
	v_lshl_add_u64 v[48:49], v[48:49], 0, v[128:129]
	global_store_dwordx4 v[104:105], v[32:35], off offset:64 sc1
	v_cvt_pk_bf16_f32 v28, v28, v29
	v_cvt_pk_bf16_f32 v29, v30, v31
	v_cvt_pk_bf16_f32 v32, v44, v45
	v_cvt_pk_bf16_f32 v33, v46, v47
	v_cvt_pk_bf16_f32 v34, v40, v41
	v_cvt_pk_bf16_f32 v35, v42, v43
	v_cvt_pk_bf16_f32 v30, v24, v25
	v_cvt_pk_bf16_f32 v31, v26, v27
	v_cvt_pk_bf16_f32 v20, v20, v21
	v_cvt_pk_bf16_f32 v21, v22, v23
	v_cvt_pk_bf16_f32 v22, v16, v17
	v_cvt_pk_bf16_f32 v23, v18, v19
	v_cvt_pk_bf16_f32 v12, v12, v13
	v_cvt_pk_bf16_f32 v13, v14, v15
	v_cvt_pk_bf16_f32 v14, v8, v9
	v_cvt_pk_bf16_f32 v15, v10, v11
	v_cvt_pk_bf16_f32 v4, v4, v5
	v_cvt_pk_bf16_f32 v5, v6, v7
	v_cvt_pk_bf16_f32 v6, v0, v1
	v_cvt_pk_bf16_f32 v7, v2, v3
	s_cmpk_lt_i32 s13, 0x400
	global_store_dwordx4 v[112:113], v[116:119], off sc1
	global_store_dwordx4 v[104:105], v[108:111], off sc1
	global_store_dwordx4 v[96:97], v[100:103], off sc1
	global_store_dwordx4 v[80:81], v[84:87], off sc1
	global_store_dwordx4 v[64:65], v[68:71], off sc1
	global_store_dwordx4 v[48:49], v[52:55], off sc1
	global_store_dwordx4 v[50:51], v[36:39], off sc1
	global_store_dwordx4 v[96:97], v[32:35], off offset:64 sc1
	global_store_dwordx4 v[80:81], v[28:31], off offset:64 sc1
	global_store_dwordx4 v[64:65], v[20:23], off offset:64 sc1
	global_store_dwordx4 v[48:49], v[12:15], off offset:64 sc1
	global_store_dwordx4 v[50:51], v[4:7], off offset:64 sc1
	s_cbranch_scc0 .LBB0_529
